# ret_out A_ret and weight-conversion stores cover full 128-byte lines per instruction (8 lanes per row); state store widened
# baseline (speedup 1.0000x reference)
; #define LAS __attribute__((address_space(3)))
; __device__ __forceinline__ void ret_out_phase(const Args& A, Frame& F, int l, bool lastl, bf16_t* ARET, bf16_t* ALRU) {
;     ...
;     for (int jx = 0; jx < nmy; ++jx) {
;         const int it = F.bid + jx * F.G, itn = (jx + 1 < nmy) ? it + F.G : it;
;         const int bh = it / NCHU, mc = it - bh * NCHU + (NCH - NCHU), h = bh & 7, b = bh >> 3;
;         const size_t rowbase = (size_t)b * TB + 128 * mc;
;         __syncthreads();
; #pragma unroll
;         for (int i = 0; i < 2; ++i) {
;             const int u = tid + i * NTHREADS, r = u >> 3, c8 = (u & 7) * 8;
;             *(LAS u32x4*)(ks_ + r * 72 + c8) = P.k[i]; *(LAS u32x4*)(sfs + r * 72 + c8) = P.sf[i]; *(LAS u32x4*)(sbs + r * 72 + c8) = P.sb[i];
;         }
; #pragma unroll
;         for (int i = 0; i < 4; ++i) { const int u = tid + i * NTHREADS, r = u >> 4, c8 = (u & 15) * 8; *(LAS u32x4*)(vts + r * 136 + c8) = P.vt[i]; }
;         bf16x8 qf[2];
; #pragma unroll
;         for (int ks = 0; ks < 2; ++ks) qf[ks] = *(const bf16x8*)(WSB(WS_Q) + (rowbase + 16 * w + fr) * 512 + h * 64 + 32 * ks + 8 * fq);
;         __syncthreads();
;         ret_prefetch(F, itn, NCHU, P);
;         const float l2f = log2_gamma(A, F, l, 0, h), l2b = log2_gamma(A, F, l, 1, h);
.LBB0_30:
	s_add_i32 s39, s39, 1
	s_cmp_lt_i32 s39, s37
	s_cselect_b32 s2, s34, 0
	s_abs_i32 s5, vcc_hi
	s_mul_hi_u32 s8, s5, s45
	s_mul_i32 s9, s8, s20
	s_sub_i32 s5, s5, s9
	s_ashr_i32 s4, vcc_hi, 31
	s_add_i32 s9, s8, 1
	s_sub_i32 s25, s5, s20
	s_cmp_ge_u32 s5, s20
	s_cselect_b32 s8, s9, s8
	s_cselect_b32 s5, s25, s5
	s_add_i32 s9, s8, 1
	s_cmp_ge_u32 s5, s20
	s_cselect_b32 s5, s9, s8
	s_xor_b32 s5, s5, s4
	s_sub_i32 s4, s5, s4
	s_not_b32 s5, s4
	s_mul_i32 s5, vcc_lo, s5
	s_ashr_i32 s8, s4, 3
	s_add_i32 s5, s61, s5
	s_ashr_i32 s9, s5, 31
	s_add_i32 s25, s2, vcc_hi
	s_mul_hi_i32 s52, s8, 0x900
	s_mulk_i32 s8, 0x900
	s_and_b32 s2, s4, 7
	s_add_u32 s8, s8, s5
	s_addc_u32 s9, s52, s9
	s_abs_i32 s5, s25
	s_mul_hi_u32 s52, s5, s45
	s_mul_i32 s53, s52, s20
	s_sub_i32 s5, s5, s53
	s_lshl_b32 s82, s2, 7
	s_ashr_i32 s4, s25, 31
	s_add_i32 s53, s52, 1
	s_sub_i32 s58, s5, s20
	s_cmp_ge_u32 s5, s20
	s_cselect_b32 s52, s53, s52
	s_cselect_b32 s5, s58, s5
	s_add_i32 s53, s52, 1
	s_cmp_ge_u32 s5, s20
	s_cselect_b32 s5, s53, s52
	s_xor_b32 s5, s5, s4
	s_sub_i32 s4, s5, s4
	s_not_b32 s5, s4
	s_mul_i32 s5, s20, s5
	s_add_i32 s5, s25, s5
	v_lshl_add_u64 v[50:51], v[122:123], 0, s[8:9]
	v_lshlrev_b64 v[50:51], 10, v[50:51]
	v_lshl_add_u64 v[50:51], s[48:49], 0, v[50:51]
	v_lshl_add_u64 v[50:51], v[50:51], 0, s[82:83]
	v_lshl_add_u64 v[50:51], v[50:51], 0, v[0:1]
	global_load_dwordx4 v[46:49], v[50:51], off
	global_load_dwordx4 v[42:45], v[50:51], off offset:64
	s_barrier
	s_waitcnt vmcnt(0)
	ds_write_b128 v134, v[6:9]
	ds_write_b128 v134, v[10:13] offset:53248
	ds_write_b128 v135, v[2:5]
	ds_write_b128 v136, v[22:25]
	ds_write_b128 v136, v[26:29] offset:53248
	ds_write_b128 v137, v[34:37]
	v_lshl_add_u64 v[2:3], v[122:123], 0, s[8:9]
	s_add_i32 s25, s5, 18
	v_lshlrev_b64 v[2:3], 10, v[2:3]
	s_ashr_i32 s5, s4, 3
	s_lshl_b32 s72, s25, 7
	v_lshl_add_u64 v[2:3], s[48:49], 0, v[2:3]
	s_mul_hi_i32 s52, s5, 0x900
	s_mulk_i32 s5, 0x900
	s_ashr_i32 s73, s72, 31
	v_lshl_add_u64 v[2:3], v[2:3], 0, s[82:83]
	s_add_u32 s92, s5, s72
	ds_write_b128 v245, v[14:17] offset:18432
	ds_write_b128 v246, v[18:21] offset:18432
	ds_write_b128 v247, v[30:33] offset:18432
	ds_write_b128 v248, v[38:41] offset:18432
	v_lshl_add_u64 v[2:3], v[2:3], 0, v[0:1]
	s_addc_u32 s93, s52, s73
	s_ashr_i32 s5, s4, 31
	s_mul_i32 s52, s4, 36
	s_ashr_i32 s58, s25, 31
	s_mul_hi_i32 s53, s4, 36
	s_add_u32 s52, s52, s25
	v_lshl_add_u64 v[2:3], s[92:93], 0, v[116:117]
	v_lshl_add_u64 v[14:15], s[92:93], 0, v[114:115]
	s_addc_u32 s53, s53, s58
	v_lshlrev_b64 v[2:3], 10, v[2:3]
	s_lshl_b32 s25, s4, 7
	v_lshlrev_b64 v[14:15], 10, v[14:15]
	s_lshl_b64 s[52:53], s[52:53], 14
	v_lshl_add_u64 v[2:3], s[6:7], 0, v[2:3]
	s_and_b32 s78, s25, 0x380
	s_mov_b32 s79, s83
	v_lshl_add_u64 v[14:15], s[6:7], 0, v[14:15]
	v_lshl_add_u64 v[2:3], v[2:3], 0, s[78:79]
	v_mov_b32_e32 v129, v1
	s_add_u32 s76, s62, s52
	v_lshl_add_u64 v[14:15], v[14:15], 0, s[78:79]
	v_lshl_add_u64 v[2:3], v[2:3], 0, v[128:129]
	s_addc_u32 s77, s63, s53
	v_lshl_add_u64 v[14:15], v[14:15], 0, v[128:129]
	s_waitcnt lgkmcnt(0)
	s_barrier
	global_load_dwordx4 v[6:9], v[2:3], off
	global_load_dwordx4 v[22:25], v[14:15], off
	v_lshl_add_u64 v[2:3], s[76:77], 0, v[120:121]
	s_add_u32 s74, s65, s52
	v_lshl_add_u64 v[14:15], s[76:77], 0, v[118:119]
	v_lshl_add_u64 v[2:3], v[2:3], 0, v[128:129]
	s_addc_u32 s75, s19, s53
	v_lshl_add_u64 v[14:15], v[14:15], 0, v[128:129]
	global_load_dwordx4 v[10:13], v[2:3], off
	global_load_dwordx4 v[26:29], v[14:15], off
	v_lshl_add_u64 v[2:3], s[74:75], 0, v[120:121]
	v_lshl_add_u64 v[14:15], s[74:75], 0, v[118:119]
	v_lshl_add_u64 v[2:3], v[2:3], 0, v[128:129]
	v_lshl_add_u64 v[14:15], v[14:15], 0, v[128:129]
	s_lshl_b64 s[74:75], s[4:5], 7
	global_load_dwordx4 v[2:5], v[2:3], off
	v_mov_b64_e32 v[38:39], s[54:55]
	global_load_dwordx4 v[34:37], v[14:15], off
	v_lshl_add_u64 v[14:15], s[74:75], 0, v[106:107]
	v_lshl_add_u64 v[18:19], s[74:75], 0, v[108:109]
	v_lshl_add_u64 v[30:31], s[74:75], 0, v[110:111]
	v_lshl_add_u64 v[50:51], s[74:75], 0, v[112:113]
	v_mad_u64_u32 v[16:17], s[4:5], v14, s96, v[38:39]
	v_mad_u64_u32 v[20:21], s[52:53], v18, s96, v[38:39]
	v_mad_u64_u32 v[32:33], s[52:53], v30, s96, v[38:39]
	v_mad_u64_u32 v[38:39], s[52:53], v50, s96, v[38:39]
	s_load_dwordx2 s[74:75], s[46:47], 0x60
	v_mad_i32_i24 v17, v15, s96, v17
	s_lshl_b64 s[4:5], s[72:73], 1
	v_mad_i32_i24 v21, v19, s96, v21
	v_mad_i32_i24 v33, v31, s96, v33
	v_mad_i32_i24 v39, v51, s96, v39
	v_lshl_add_u64 v[14:15], v[16:17], 0, s[4:5]
	v_lshl_add_u64 v[18:19], v[20:21], 0, s[4:5]
	v_lshl_add_u64 v[30:31], v[32:33], 0, s[4:5]
	v_lshl_add_u64 v[38:39], v[38:39], 0, s[4:5]
	s_or_b32 s4, s2, s64
	s_ashr_i32 s5, s4, 31
	s_lshl_b64 s[4:5], s[4:5], 2
	s_waitcnt lgkmcnt(0)
	s_add_u32 s78, s74, s4
	s_addc_u32 s79, s75, s5
	s_load_dword s98, s[78:79], 0x0
	s_load_dword s99, s[78:79], 0x20
	s_mov_b32 s76, 0xb2a5705f
	s_mov_b32 s77, 0x42ce8ed0
	s_mov_b32 s58, 0xc2b17218
	s_mov_b32 s25, 0x3f2aaaab
	s_mov_b32 s72, 0x7f800000
	s_mov_b32 s73, 0x33800000
	v_lshlrev_b32_e32 v40, 1, v104
	v_mov_b32_e32 v41, v1
	v_lshl_add_u64 v[14:15], v[14:15], 0, v[40:41]
	v_lshl_add_u64 v[18:19], v[18:19], 0, v[40:41]
	v_lshl_add_u64 v[30:31], v[30:31], 0, v[40:41]
	v_lshl_add_u64 v[38:39], v[38:39], 0, v[40:41]
	global_load_dwordx4 v[14:17], v[14:15], off
	v_readlane_b32 s4, v254, 38
	global_load_dwordx4 v[18:21], v[18:19], off
	v_readlane_b32 s5, v254, 39
	global_load_dwordx4 v[30:33], v[30:31], off
	v_add_u32_e32 v82, 0x4800, v230
	global_load_dwordx4 v[38:41], v[38:39], off
	s_mov_b32 s53, s64
	s_waitcnt vmcnt(10) lgkmcnt(0)
; #define LAS __attribute__((address_space(3)))
; __device__ __forceinline__ unsigned pk2(float lo, float hi) { const f32x2_t v = {lo, hi}; const bf16v2_t b = __builtin_convertvector(v, bf16v2_t); return __builtin_bit_cast(unsigned, b); }
; __device__ __forceinline__ float softplusf_(float x) { return fmaxf(x, 0.f) + log1pf(expf(-fabsf(x))); }
; __device__ __forceinline__ float log2_gamma(const Args& A, const Frame& F, int l, int dir, int h) {
;     const float x = GIN(12)[(l * 2 + dir) * NH + h];
;     return -softplusf_(-x) * 1.4426950408889634f;
; }
; __device__ __forceinline__ void ret_out_phase(const Args& A, Frame& F, int l, bool lastl, bf16_t* ARET, bf16_t* ALRU) {
;     ...
;         const float l2f = log2_gamma(A, F, l, 0, h), l2b = log2_gamma(A, F, l, 1, h);
;         bf16x8 pa[4];
;         {
;             const int i_loc = 16 * w + fr;
; #pragma unroll
;             for (int jp = 0; jp < 4; ++jp) {
;                 f32x4 c0 = (f32x4){0.f, 0.f, 0.f, 0.f}, c1 = c0;
; #pragma unroll
;                 for (int ks = 0; ks < 2; ++ks) {
;                     const bf16x8 k0 = *(const LAS bf16x8*)(ks_ + (32 * jp + fr) * 72 + 32 * ks + 8 * fq);
;                     const bf16x8 k1 = *(const LAS bf16x8*)(ks_ + (32 * jp + 16 + fr) * 72 + 32 * ks + 8 * fq);
;                     c0 = __builtin_amdgcn_mfma_f32_16x16x32_bf16(k0, qf[ks], c0, 0, 0, 0);
;                     c1 = __builtin_amdgcn_mfma_f32_16x16x32_bf16(k1, qf[ks], c1, 0, 0, 0);
;                 }
;                 float v[8];
; #pragma unroll
;                 for (int r = 0; r < 4; ++r) {
;                     const int j0 = 32 * jp + 4 * fq + r, j1 = j0 + 16;
;                     const int d0 = i_loc - j0, d1 = i_loc - j1;
;                     v[r] = c0[r] * (d0 >= 0 ? exp2f((float)d0 * l2f) : exp2f((float)(-d0) * l2b));
;                     v[4 + r] = c1[r] * (d1 >= 0 ? exp2f((float)d1 * l2f) : exp2f((float)(-d1) * l2b));
;                 }
;                 u32x4 pv; pv[0] = pk2(v[0], v[1]); pv[1] = pk2(v[2], v[3]); pv[2] = pk2(v[4], v[5]); pv[3] = pk2(v[6], v[7]);
;                 pa[jp] = __builtin_bit_cast(bf16x8, pv);
;             }
	s_mov_b32 s100, 0x3c800000
	v_mov_b32_e32 v50, s98
	v_and_b32_e32 v51, 0x7fffffff, v50
	v_mul_f32_e32 v51, 0xbfb8aa3b, v51
	v_exp_f32_e32 v51, v51
	v_mov_b32_e32 v52, 0x3e4ccccd
	v_fmaak_f32 v52, v51, v52, 0xbe800000
	v_fmaak_f32 v52, v51, v52, 0x3eaaaaab
	v_fmaak_f32 v52, v51, v52, 0xbf000000
	v_fmaak_f32 v52, v51, v52, 0x3f800000
	v_mul_f32_e32 v52, v51, v52
	v_add_f32_e32 v53, 1.0, v51
	v_log_f32_e32 v53, v53
	v_cmp_gt_f32_e64 s[74:75], s100, v51
	v_mul_f32_e32 v53, 0x3f317218, v53
	s_nop 1
	v_cndmask_b32_e64 v52, v53, v52, s[74:75]
	v_max_f32_e64 v53, -v50, 0
	v_add_f32_e32 v52, v53, v52
	v_mul_f32_e32 v66, 0xbfb8aa3b, v52
	v_mov_b32_e32 v54, s99
	v_and_b32_e32 v55, 0x7fffffff, v54
	v_mul_f32_e32 v55, 0xbfb8aa3b, v55
	v_exp_f32_e32 v55, v55
	v_mov_b32_e32 v56, 0x3e4ccccd
	v_fmaak_f32 v56, v55, v56, 0xbe800000
	v_fmaak_f32 v56, v55, v56, 0x3eaaaaab
	v_fmaak_f32 v56, v55, v56, 0xbf000000
	v_fmaak_f32 v56, v55, v56, 0x3f800000
	v_mul_f32_e32 v56, v55, v56
	v_add_f32_e32 v57, 1.0, v55
	v_log_f32_e32 v57, v57
	v_cmp_gt_f32_e64 s[74:75], s100, v55
	v_mul_f32_e32 v57, 0x3f317218, v57
	s_nop 1
	v_cndmask_b32_e64 v56, v57, v56, s[74:75]
	v_max_f32_e64 v57, -v54, 0
	v_add_f32_e32 v56, v57, v56
	v_mul_f32_e32 v67, 0xbfb8aa3b, v56
	ds_read_b128 v[50:53], v143
	ds_read_b128 v[54:57], v143 offset:2304
	s_waitcnt lgkmcnt(1)
	v_mfma_f32_16x16x32_bf16 v[50:53], v[50:53], v[46:49], 0
	ds_read_b128 v[58:61], v143 offset:64
	ds_read_b128 v[62:65], v143 offset:2368
	s_waitcnt lgkmcnt(1)
	v_mfma_f32_16x16x32_bf16 v[50:53], v[58:61], v[42:45], v[50:53]
	v_mul_f32_e32 v58, v67, v144
	v_mul_f32_e32 v59, v66, v145
	v_cndmask_b32_e64 v58, v59, v58, s[4:5]
	v_cmp_gt_f32_e64 s[74:75], s3, v58
	v_readlane_b32 s4, v254, 36
	v_mul_f32_e32 v60, v66, v147
	v_cndmask_b32_e64 v59, 0, v183, s[74:75]
	v_add_f32_e32 v58, v58, v59
	v_exp_f32_e32 v58, v58
	v_cndmask_b32_e64 v59, 0, v184, s[74:75]
	v_readlane_b32 s5, v254, 37
	v_mul_f32_e32 v61, v67, v148
	v_ldexp_f32 v58, v58, v59
	v_mul_f32_e32 v59, v67, v146
	v_cndmask_b32_e64 v59, v60, v59, s[4:5]
	v_cmp_gt_f32_e64 s[74:75], s3, v59
	v_readlane_b32 s4, v254, 40
	v_readlane_b32 s5, v254, 41
	v_cndmask_b32_e64 v60, 0, v183, s[74:75]
	v_add_f32_e32 v59, v59, v60
	v_exp_f32_e32 v59, v59
	v_cndmask_b32_e64 v60, 0, v184, s[74:75]
	v_mfma_f32_16x16x32_bf16 v[54:57], v[54:57], v[46:49], 0
	v_ldexp_f32 v60, v59, v60
	v_mul_f32_e32 v59, v66, v149
	v_cndmask_b32_e64 v59, v59, v61, s[4:5]
	v_cmp_gt_f32_e64 s[74:75], s3, v59
	v_readlane_b32 s4, v254, 42
	v_readlane_b32 s5, v254, 43
	v_cndmask_b32_e64 v61, 0, v183, s[74:75]
	v_add_f32_e32 v59, v59, v61
	v_exp_f32_e32 v59, v59
	v_cndmask_b32_e64 v61, 0, v184, s[74:75]
	s_waitcnt lgkmcnt(0)
	v_mfma_f32_16x16x32_bf16 v[54:57], v[62:65], v[42:45], v[54:57]
	v_ldexp_f32 v59, v59, v61
	v_pk_mul_f32 v[50:51], v[50:51], v[58:59]
	v_mul_f32_e32 v58, v66, v151
	v_mul_f32_e32 v59, v67, v150
	v_cndmask_b32_e64 v58, v58, v59, s[4:5]
	v_cmp_gt_f32_e64 s[74:75], s3, v58
	v_readlane_b32 s4, v254, 44
	v_readlane_b32 s5, v254, 45
	v_cndmask_b32_e64 v59, 0, v183, s[74:75]
	v_add_f32_e32 v58, v58, v59
	v_exp_f32_e32 v58, v58
	v_cndmask_b32_e64 v59, 0, v184, s[74:75]
	v_cvt_pk_bf16_f32 v50, v50, v51
	v_ldexp_f32 v61, v58, v59
	v_mul_f32_e32 v58, v66, v153
	v_mul_f32_e32 v59, v67, v152
	v_cndmask_b32_e64 v58, v58, v59, s[4:5]
	v_cmp_gt_f32_e64 s[74:75], s3, v58
	v_readlane_b32 s4, v254, 46
	v_pk_mul_f32 v[54:55], v[54:55], v[60:61]
	v_cndmask_b32_e64 v59, 0, v183, s[74:75]
	v_add_f32_e32 v58, v58, v59
	v_exp_f32_e32 v58, v58
	v_cndmask_b32_e64 v59, 0, v184, s[74:75]
	v_mul_f32_e32 v60, v67, v154
	v_readlane_b32 s5, v254, 47
	v_ldexp_f32 v58, v58, v59
	v_mul_f32_e32 v59, v66, v155
	v_cndmask_b32_e64 v59, v59, v60, s[4:5]
	v_cmp_gt_f32_e64 s[74:75], s3, v59
	v_readlane_b32 s4, v254, 48
	v_mul_f32_e32 v61, v67, v156
	v_cndmask_b32_e64 v60, 0, v183, s[74:75]
	v_add_f32_e32 v59, v59, v60
	v_exp_f32_e32 v59, v59
	v_cndmask_b32_e64 v60, 0, v184, s[74:75]
	v_readlane_b32 s5, v254, 49
	v_ldexp_f32 v60, v59, v60
	v_mul_f32_e32 v59, v66, v157
	v_cndmask_b32_e64 v59, v59, v61, s[4:5]
	v_cmp_gt_f32_e64 s[74:75], s3, v59
	v_readlane_b32 s4, v254, 50
	v_readlane_b32 s5, v254, 51
	v_cndmask_b32_e64 v61, 0, v183, s[74:75]
	v_add_f32_e32 v59, v59, v61
	v_exp_f32_e32 v59, v59
	v_cndmask_b32_e64 v61, 0, v184, s[74:75]
	v_ldexp_f32 v59, v59, v61
	v_pk_mul_f32 v[52:53], v[52:53], v[58:59]
	v_mul_f32_e32 v58, v66, v159
	v_mul_f32_e32 v59, v67, v158
	v_cndmask_b32_e64 v58, v58, v59, s[4:5]
	v_cmp_gt_f32_e64 s[74:75], s3, v58
	v_cvt_pk_bf16_f32 v51, v52, v53
	v_cvt_pk_bf16_f32 v52, v54, v55
	v_cndmask_b32_e64 v59, 0, v183, s[74:75]
	v_add_f32_e32 v58, v58, v59
	v_exp_f32_e32 v58, v58
	v_cndmask_b32_e64 v59, 0, v184, s[74:75]
	v_readlane_b32 s4, v254, 52
	v_readlane_b32 s5, v254, 53
	v_ldexp_f32 v61, v58, v59
	v_pk_mul_f32 v[56:57], v[56:57], v[60:61]
	s_nop 0
	v_cvt_pk_bf16_f32 v53, v56, v57
	ds_read_b128 v[54:57], v160
	ds_read_b128 v[58:61], v160 offset:2304
	s_waitcnt lgkmcnt(1)
	v_mfma_f32_16x16x32_bf16 v[54:57], v[54:57], v[46:49], 0
	ds_read_b128 v[62:65], v160 offset:64
	ds_read_b128 v[68:71], v160 offset:2368
	s_waitcnt lgkmcnt(1)
; #define LAS __attribute__((address_space(3)))
; __device__ __forceinline__ unsigned pk2(float lo, float hi) { const f32x2_t v = {lo, hi}; const bf16v2_t b = __builtin_convertvector(v, bf16v2_t); return __builtin_bit_cast(unsigned, b); }
; __device__ __forceinline__ void ret_out_phase(const Args& A, Frame& F, int l, bool lastl, bf16_t* ARET, bf16_t* ALRU) {
;     ...
;             for (int jp = 0; jp < 4; ++jp) {
;                 f32x4 c0 = (f32x4){0.f, 0.f, 0.f, 0.f}, c1 = c0;
; #pragma unroll
;                 for (int ks = 0; ks < 2; ++ks) {
;                     const bf16x8 k0 = *(const LAS bf16x8*)(ks_ + (32 * jp + fr) * 72 + 32 * ks + 8 * fq);
;                     const bf16x8 k1 = *(const LAS bf16x8*)(ks_ + (32 * jp + 16 + fr) * 72 + 32 * ks + 8 * fq);
;                     c0 = __builtin_amdgcn_mfma_f32_16x16x32_bf16(k0, qf[ks], c0, 0, 0, 0);
;                     c1 = __builtin_amdgcn_mfma_f32_16x16x32_bf16(k1, qf[ks], c1, 0, 0, 0);
;                 }
;                 float v[8];
; #pragma unroll
;                 for (int r = 0; r < 4; ++r) {
;                     const int j0 = 32 * jp + 4 * fq + r, j1 = j0 + 16;
;                     const int d0 = i_loc - j0, d1 = i_loc - j1;
;                     v[r] = c0[r] * (d0 >= 0 ? exp2f((float)d0 * l2f) : exp2f((float)(-d0) * l2b));
;                     v[4 + r] = c1[r] * (d1 >= 0 ? exp2f((float)d1 * l2f) : exp2f((float)(-d1) * l2b));
;                 }
;                 u32x4 pv; pv[0] = pk2(v[0], v[1]); pv[1] = pk2(v[2], v[3]); pv[2] = pk2(v[4], v[5]); pv[3] = pk2(v[6], v[7]);
;                 pa[jp] = __builtin_bit_cast(bf16x8, pv);
;             }
	v_mfma_f32_16x16x32_bf16 v[54:57], v[62:65], v[42:45], v[54:57]
	v_mul_f32_e32 v62, v66, v162
	v_mul_f32_e32 v63, v67, v161
	v_cndmask_b32_e64 v62, v62, v63, s[4:5]
	v_cmp_gt_f32_e64 s[74:75], s3, v62
	v_readlane_b32 s4, v254, 54
	v_mul_f32_e32 v64, v67, v163
	v_cndmask_b32_e64 v63, 0, v183, s[74:75]
	v_add_f32_e32 v62, v62, v63
	v_exp_f32_e32 v62, v62
	v_cndmask_b32_e64 v63, 0, v184, s[74:75]
	v_readlane_b32 s5, v254, 55
	v_mul_f32_e32 v65, v67, v165
	v_ldexp_f32 v62, v62, v63
	v_mul_f32_e32 v63, v66, v164
	v_cndmask_b32_e64 v63, v63, v64, s[4:5]
	v_cmp_gt_f32_e64 s[74:75], s3, v63
	v_readlane_b32 s4, v254, 56
	v_readlane_b32 s5, v254, 57
	v_cndmask_b32_e64 v64, 0, v183, s[74:75]
	v_add_f32_e32 v63, v63, v64
	v_exp_f32_e32 v63, v63
	v_cndmask_b32_e64 v64, 0, v184, s[74:75]
	v_mfma_f32_16x16x32_bf16 v[58:61], v[58:61], v[46:49], 0
	v_ldexp_f32 v64, v63, v64
	v_mul_f32_e32 v63, v66, v166
	v_cndmask_b32_e64 v63, v63, v65, s[4:5]
	v_cmp_gt_f32_e64 s[74:75], s3, v63
	v_readlane_b32 s4, v254, 58
	v_readlane_b32 s5, v254, 59
	v_cndmask_b32_e64 v65, 0, v183, s[74:75]
	v_add_f32_e32 v63, v63, v65
	v_exp_f32_e32 v63, v63
	v_cndmask_b32_e64 v65, 0, v184, s[74:75]
	s_waitcnt lgkmcnt(0)
	v_mfma_f32_16x16x32_bf16 v[58:61], v[68:71], v[42:45], v[58:61]
	v_ldexp_f32 v63, v63, v65
	v_pk_mul_f32 v[54:55], v[54:55], v[62:63]
	v_mul_f32_e32 v62, v66, v168
	v_mul_f32_e32 v63, v67, v167
	v_cndmask_b32_e64 v62, v62, v63, s[4:5]
	v_cmp_gt_f32_e64 s[74:75], s3, v62
	v_readlane_b32 s4, v254, 60
	v_readlane_b32 s5, v254, 61
	v_cndmask_b32_e64 v63, 0, v183, s[74:75]
	v_add_f32_e32 v62, v62, v63
	v_exp_f32_e32 v62, v62
	v_cndmask_b32_e64 v63, 0, v184, s[74:75]
	v_cvt_pk_bf16_f32 v54, v54, v55
	v_ldexp_f32 v65, v62, v63
	v_mul_f32_e32 v62, v66, v189
	v_mul_f32_e32 v63, v67, v169
	v_cndmask_b32_e64 v62, v62, v63, s[4:5]
	v_cmp_gt_f32_e64 s[74:75], s3, v62
	v_readlane_b32 s4, v254, 62
	v_pk_mul_f32 v[58:59], v[58:59], v[64:65]
	v_cndmask_b32_e64 v63, 0, v183, s[74:75]
	v_add_f32_e32 v62, v62, v63
	v_exp_f32_e32 v62, v62
	v_cndmask_b32_e64 v63, 0, v184, s[74:75]
	v_mul_f32_e32 v64, v67, v190
	v_readlane_b32 s5, v254, 63
	v_ldexp_f32 v62, v62, v63
	v_mul_f32_e32 v63, v66, v191
	v_cndmask_b32_e64 v63, v63, v64, s[4:5]
	v_cmp_gt_f32_e64 s[74:75], s3, v63
	v_readlane_b32 s4, v255, 0
	v_mul_f32_e32 v65, v67, v192
	v_cndmask_b32_e64 v64, 0, v183, s[74:75]
	v_add_f32_e32 v63, v63, v64
	v_exp_f32_e32 v63, v63
	v_cndmask_b32_e64 v64, 0, v184, s[74:75]
	v_readlane_b32 s5, v255, 1
	v_ldexp_f32 v64, v63, v64
	v_mul_f32_e32 v63, v66, v193
	v_cndmask_b32_e64 v63, v63, v65, s[4:5]
	v_cmp_gt_f32_e64 s[74:75], s3, v63
	v_readlane_b32 s4, v255, 2
	v_readlane_b32 s5, v255, 3
	v_cndmask_b32_e64 v65, 0, v183, s[74:75]
	v_add_f32_e32 v63, v63, v65
	v_exp_f32_e32 v63, v63
	v_cndmask_b32_e64 v65, 0, v184, s[74:75]
	v_ldexp_f32 v63, v63, v65
	v_pk_mul_f32 v[56:57], v[56:57], v[62:63]
	v_mul_f32_e32 v62, v66, v195
	v_mul_f32_e32 v63, v67, v194
	v_cndmask_b32_e64 v62, v62, v63, s[4:5]
	v_cmp_gt_f32_e64 s[74:75], s3, v62
	v_cvt_pk_bf16_f32 v55, v56, v57
	v_cvt_pk_bf16_f32 v56, v58, v59
	v_cndmask_b32_e64 v63, 0, v183, s[74:75]
	v_add_f32_e32 v62, v62, v63
	v_exp_f32_e32 v62, v62
	v_cndmask_b32_e64 v63, 0, v184, s[74:75]
	v_readlane_b32 s4, v255, 4
	v_readlane_b32 s5, v255, 5
	v_ldexp_f32 v65, v62, v63
	v_pk_mul_f32 v[60:61], v[60:61], v[64:65]
	s_nop 0
	v_cvt_pk_bf16_f32 v57, v60, v61
	ds_read_b128 v[58:61], v196
	ds_read_b128 v[62:65], v196 offset:2304
	s_waitcnt lgkmcnt(1)
	v_mfma_f32_16x16x32_bf16 v[58:61], v[58:61], v[46:49], 0
	ds_read_b128 v[68:71], v196 offset:64
	ds_read_b128 v[72:75], v196 offset:2368
	s_waitcnt lgkmcnt(1)
	v_mfma_f32_16x16x32_bf16 v[58:61], v[68:71], v[42:45], v[58:61]
	v_mul_f32_e32 v68, v66, v198
	v_mul_f32_e32 v69, v67, v197
	v_cndmask_b32_e64 v68, v68, v69, s[4:5]
	v_cmp_gt_f32_e64 s[74:75], s3, v68
	v_readlane_b32 s4, v255, 6
	v_mul_f32_e32 v70, v67, v199
	v_cndmask_b32_e64 v69, 0, v183, s[74:75]
	v_add_f32_e32 v68, v68, v69
	v_exp_f32_e32 v68, v68
	v_cndmask_b32_e64 v69, 0, v184, s[74:75]
	v_readlane_b32 s5, v255, 7
	v_mul_f32_e32 v71, v67, v201
	v_ldexp_f32 v68, v68, v69
	v_mul_f32_e32 v69, v66, v200
	v_cndmask_b32_e64 v69, v69, v70, s[4:5]
	v_cmp_gt_f32_e64 s[74:75], s3, v69
	v_readlane_b32 s4, v255, 8
	v_readlane_b32 s5, v255, 9
	v_cndmask_b32_e64 v70, 0, v183, s[74:75]
	v_add_f32_e32 v69, v69, v70
	v_exp_f32_e32 v69, v69
	v_cndmask_b32_e64 v70, 0, v184, s[74:75]
	v_mfma_f32_16x16x32_bf16 v[62:65], v[62:65], v[46:49], 0
	v_ldexp_f32 v70, v69, v70
	v_mul_f32_e32 v69, v66, v202
	v_cndmask_b32_e64 v69, v69, v71, s[4:5]
	v_cmp_gt_f32_e64 s[74:75], s3, v69
	v_readlane_b32 s4, v255, 10
	v_readlane_b32 s5, v255, 11
	v_cndmask_b32_e64 v71, 0, v183, s[74:75]
	v_add_f32_e32 v69, v69, v71
	v_exp_f32_e32 v69, v69
	v_cndmask_b32_e64 v71, 0, v184, s[74:75]
	s_waitcnt lgkmcnt(0)
; #define LAS __attribute__((address_space(3)))
; __device__ __forceinline__ unsigned pk2(float lo, float hi) { const f32x2_t v = {lo, hi}; const bf16v2_t b = __builtin_convertvector(v, bf16v2_t); return __builtin_bit_cast(unsigned, b); }
; __device__ __forceinline__ void ret_out_phase(const Args& A, Frame& F, int l, bool lastl, bf16_t* ARET, bf16_t* ALRU) {
;     ...
;             for (int jp = 0; jp < 4; ++jp) {
;                 f32x4 c0 = (f32x4){0.f, 0.f, 0.f, 0.f}, c1 = c0;
; #pragma unroll
;                 for (int ks = 0; ks < 2; ++ks) {
;                     const bf16x8 k0 = *(const LAS bf16x8*)(ks_ + (32 * jp + fr) * 72 + 32 * ks + 8 * fq);
;                     const bf16x8 k1 = *(const LAS bf16x8*)(ks_ + (32 * jp + 16 + fr) * 72 + 32 * ks + 8 * fq);
;                     c0 = __builtin_amdgcn_mfma_f32_16x16x32_bf16(k0, qf[ks], c0, 0, 0, 0);
;                     c1 = __builtin_amdgcn_mfma_f32_16x16x32_bf16(k1, qf[ks], c1, 0, 0, 0);
;                 }
;                 float v[8];
; #pragma unroll
;                 for (int r = 0; r < 4; ++r) {
;                     const int j0 = 32 * jp + 4 * fq + r, j1 = j0 + 16;
;                     const int d0 = i_loc - j0, d1 = i_loc - j1;
;                     v[r] = c0[r] * (d0 >= 0 ? exp2f((float)d0 * l2f) : exp2f((float)(-d0) * l2b));
;                     v[4 + r] = c1[r] * (d1 >= 0 ? exp2f((float)d1 * l2f) : exp2f((float)(-d1) * l2b));
;                 }
;                 u32x4 pv; pv[0] = pk2(v[0], v[1]); pv[1] = pk2(v[2], v[3]); pv[2] = pk2(v[4], v[5]); pv[3] = pk2(v[6], v[7]);
;                 pa[jp] = __builtin_bit_cast(bf16x8, pv);
;             }
;         }
;         bf16x8 qF[2], qB[2];
;         {
;             const int il = 16 * w + fr;
;             const float sF = exp2f((float)(il + 1) * l2f), sB = exp2f((float)(128 - il) * l2b);
; #pragma unroll
;             for (int ks = 0; ks < 2; ++ks) { qF[ks] = scale1(qf[ks], sF); qB[ks] = scale1(qf[ks], sB); }
	v_mfma_f32_16x16x32_bf16 v[62:65], v[72:75], v[42:45], v[62:65]
	v_ldexp_f32 v69, v69, v71
	v_pk_mul_f32 v[58:59], v[58:59], v[68:69]
	v_mul_f32_e32 v68, v66, v204
	v_mul_f32_e32 v69, v67, v203
	v_cndmask_b32_e64 v68, v68, v69, s[4:5]
	v_cmp_gt_f32_e64 s[74:75], s3, v68
	v_readlane_b32 s4, v255, 12
	v_readlane_b32 s5, v255, 13
	v_cndmask_b32_e64 v69, 0, v183, s[74:75]
	v_add_f32_e32 v68, v68, v69
	v_exp_f32_e32 v68, v68
	v_cndmask_b32_e64 v69, 0, v184, s[74:75]
	v_cvt_pk_bf16_f32 v58, v58, v59
	v_ldexp_f32 v71, v68, v69
	v_mul_f32_e32 v68, v66, v206
	v_mul_f32_e32 v69, v67, v205
	v_cndmask_b32_e64 v68, v68, v69, s[4:5]
	v_cmp_gt_f32_e64 s[74:75], s3, v68
	v_readlane_b32 s4, v255, 14
	v_pk_mul_f32 v[62:63], v[62:63], v[70:71]
	v_cndmask_b32_e64 v69, 0, v183, s[74:75]
	v_add_f32_e32 v68, v68, v69
	v_exp_f32_e32 v68, v68
	v_cndmask_b32_e64 v69, 0, v184, s[74:75]
	v_mul_f32_e32 v70, v67, v207
	v_readlane_b32 s5, v255, 15
	v_ldexp_f32 v68, v68, v69
	v_mul_f32_e32 v69, v66, v208
	v_cndmask_b32_e64 v69, v69, v70, s[4:5]
	v_cmp_gt_f32_e64 s[74:75], s3, v69
	v_readlane_b32 s4, v255, 16
	v_mul_f32_e32 v71, v67, v209
	v_cndmask_b32_e64 v70, 0, v183, s[74:75]
	v_add_f32_e32 v69, v69, v70
	v_exp_f32_e32 v69, v69
	v_cndmask_b32_e64 v70, 0, v184, s[74:75]
	v_readlane_b32 s5, v255, 17
	v_ldexp_f32 v70, v69, v70
	v_mul_f32_e32 v69, v66, v210
	v_cndmask_b32_e64 v69, v69, v71, s[4:5]
	v_cmp_gt_f32_e64 s[74:75], s3, v69
	v_readlane_b32 s4, v255, 18
	v_readlane_b32 s5, v255, 19
	v_cndmask_b32_e64 v71, 0, v183, s[74:75]
	v_add_f32_e32 v69, v69, v71
	v_exp_f32_e32 v69, v69
	v_cndmask_b32_e64 v71, 0, v184, s[74:75]
	v_ldexp_f32 v69, v69, v71
	v_pk_mul_f32 v[60:61], v[60:61], v[68:69]
	v_mul_f32_e32 v68, v66, v212
	v_mul_f32_e32 v69, v67, v211
	v_cndmask_b32_e64 v68, v68, v69, s[4:5]
	v_cmp_gt_f32_e64 s[74:75], s3, v68
	v_cvt_pk_bf16_f32 v59, v60, v61
	v_cvt_pk_bf16_f32 v60, v62, v63
	v_cndmask_b32_e64 v69, 0, v183, s[74:75]
	v_add_f32_e32 v68, v68, v69
	v_exp_f32_e32 v68, v68
	v_cndmask_b32_e64 v69, 0, v184, s[74:75]
	v_readlane_b32 s4, v255, 20
	v_readlane_b32 s5, v255, 21
	v_ldexp_f32 v71, v68, v69
	v_pk_mul_f32 v[64:65], v[64:65], v[70:71]
	s_nop 0
	v_cvt_pk_bf16_f32 v61, v64, v65
	ds_read_b128 v[62:65], v213
	ds_read_b128 v[68:71], v213 offset:2304
	s_waitcnt lgkmcnt(1)
	v_mfma_f32_16x16x32_bf16 v[62:65], v[62:65], v[46:49], 0
	ds_read_b128 v[72:75], v213 offset:64
	ds_read_b128 v[76:79], v213 offset:2368
	s_waitcnt lgkmcnt(1)
	v_mfma_f32_16x16x32_bf16 v[62:65], v[72:75], v[42:45], v[62:65]
	v_mul_f32_e32 v72, v66, v215
	v_mul_f32_e32 v73, v67, v214
	v_cndmask_b32_e64 v72, v72, v73, s[4:5]
	v_cmp_gt_f32_e64 s[74:75], s3, v72
	v_readlane_b32 s4, v255, 22
	v_mul_f32_e32 v74, v67, v216
	v_cndmask_b32_e64 v73, 0, v183, s[74:75]
	v_add_f32_e32 v72, v72, v73
	v_exp_f32_e32 v72, v72
	v_cndmask_b32_e64 v73, 0, v184, s[74:75]
	v_readlane_b32 s5, v255, 23
	v_mul_f32_e32 v75, v67, v218
	v_ldexp_f32 v72, v72, v73
	v_mul_f32_e32 v73, v66, v217
	v_cndmask_b32_e64 v73, v73, v74, s[4:5]
	v_cmp_gt_f32_e64 s[74:75], s3, v73
	v_readlane_b32 s4, v255, 24
	v_readlane_b32 s5, v255, 25
	v_cndmask_b32_e64 v74, 0, v183, s[74:75]
	v_add_f32_e32 v73, v73, v74
	v_exp_f32_e32 v73, v73
	v_cndmask_b32_e64 v74, 0, v184, s[74:75]
	v_mfma_f32_16x16x32_bf16 v[68:71], v[68:71], v[46:49], 0
	v_ldexp_f32 v74, v73, v74
	v_mul_f32_e32 v73, v66, v219
	v_cndmask_b32_e64 v73, v73, v75, s[4:5]
	v_cmp_gt_f32_e64 s[74:75], s3, v73
	v_readlane_b32 s4, v255, 26
	v_readlane_b32 s5, v255, 27
	v_cndmask_b32_e64 v75, 0, v183, s[74:75]
	v_add_f32_e32 v73, v73, v75
	v_exp_f32_e32 v73, v73
	v_cndmask_b32_e64 v75, 0, v184, s[74:75]
	s_waitcnt lgkmcnt(0)
	v_mfma_f32_16x16x32_bf16 v[68:71], v[76:79], v[42:45], v[68:71]
	v_ldexp_f32 v73, v73, v75
	v_pk_mul_f32 v[62:63], v[62:63], v[72:73]
	v_mul_f32_e32 v72, v66, v221
	v_mul_f32_e32 v73, v67, v220
	v_cndmask_b32_e64 v72, v72, v73, s[4:5]
	v_cmp_gt_f32_e64 s[74:75], s3, v72
	v_readlane_b32 s4, v255, 28
	v_readlane_b32 s5, v255, 29
	v_cndmask_b32_e64 v73, 0, v183, s[74:75]
	v_add_f32_e32 v72, v72, v73
	v_exp_f32_e32 v72, v72
	v_cndmask_b32_e64 v73, 0, v184, s[74:75]
	v_cvt_pk_bf16_f32 v62, v62, v63
	v_ldexp_f32 v75, v72, v73
	v_mul_f32_e32 v72, v66, v223
	v_mul_f32_e32 v73, v67, v222
	v_cndmask_b32_e64 v72, v72, v73, s[4:5]
	v_cmp_gt_f32_e64 s[74:75], s3, v72
	v_pk_mul_f32 v[68:69], v[68:69], v[74:75]
	v_mul_f32_e32 v74, v67, v224
	v_cndmask_b32_e64 v73, 0, v183, s[74:75]
	v_add_f32_e32 v72, v72, v73
	v_exp_f32_e32 v72, v72
	v_cndmask_b32_e64 v73, 0, v184, s[74:75]
	v_mul_f32_e32 v75, v67, v226
	v_ldexp_f32 v72, v72, v73
	v_mul_f32_e32 v73, v66, v225
	v_cndmask_b32_e64 v73, v73, v74, s[66:67]
	v_cmp_gt_f32_e64 s[74:75], s3, v73
	s_nop 1
	v_cndmask_b32_e64 v74, 0, v183, s[74:75]
	v_add_f32_e32 v73, v73, v74
	v_exp_f32_e32 v73, v73
	v_cndmask_b32_e64 v74, 0, v184, s[74:75]
	v_ldexp_f32 v74, v73, v74
	v_mul_f32_e32 v73, v66, v227
	v_cndmask_b32_e64 v73, v73, v75, s[68:69]
	v_cmp_gt_f32_e64 s[74:75], s3, v73
	s_nop 1
	v_cndmask_b32_e64 v75, 0, v183, s[74:75]
	v_add_f32_e32 v73, v73, v75
	v_exp_f32_e32 v73, v73
	v_cndmask_b32_e64 v75, 0, v184, s[74:75]
	v_ldexp_f32 v73, v73, v75
	v_pk_mul_f32 v[64:65], v[64:65], v[72:73]
	v_mul_f32_e32 v72, v66, v229
	v_mul_f32_e32 v73, v67, v228
	v_cndmask_b32_e64 v72, v72, v73, s[70:71]
	v_cmp_gt_f32_e64 s[74:75], s3, v72
	v_cvt_pk_bf16_f32 v63, v64, v65
	v_cvt_pk_bf16_f32 v64, v68, v69
	v_cndmask_b32_e64 v73, 0, v183, s[74:75]
	v_mul_f32_e32 v68, v66, v103
	v_add_f32_e32 v72, v72, v73
	v_cndmask_b32_e64 v73, 0, v184, s[74:75]
	v_cmp_gt_f32_e64 s[74:75], s3, v68
	v_exp_f32_e32 v72, v72
	v_and_b32_e32 v69, 0xffff0000, v46
; #define LAS __attribute__((address_space(3)))
; __device__ __forceinline__ void ret_out_phase(const Args& A, Frame& F, int l, bool lastl, bf16_t* ARET, bf16_t* ALRU) {
;     ...
;         bf16x8 qF[2], qB[2];
;         {
;             const int il = 16 * w + fr;
;             const float sF = exp2f((float)(il + 1) * l2f), sB = exp2f((float)(128 - il) * l2b);
; #pragma unroll
;             for (int ks = 0; ks < 2; ++ks) { qF[ks] = scale1(qf[ks], sF); qB[ks] = scale1(qf[ks], sB); }
;         }
;         f32x4 O[8];
; #pragma unroll
;         for (int dvt = 0; dvt < 8; ++dvt) {
;             f32x4 o = (f32x4){0.f, 0.f, 0.f, 0.f};
; #pragma unroll
;             for (int jp = 0; jp < 4; ++jp) {
;                 const u32x2 lo = *(const LAS u32x2*)(vts + (16 * dvt + fr) * 136 + 32 * jp + 4 * fq);
;                 const u32x2 hi = *(const LAS u32x2*)(vts + (16 * dvt + fr) * 136 + 32 * jp + 16 + 4 * fq);
;                 u32x4 bv; bv[0] = lo.x; bv[1] = lo.y; bv[2] = hi.x; bv[3] = hi.y;
;                 o = __builtin_amdgcn_mfma_f32_16x16x32_bf16(pa[jp], __builtin_bit_cast(bf16x8, bv), o, 0, 0, 0);
;             }
; #pragma unroll
;             for (int ks = 0; ks < 2; ++ks) {
;                 const bf16x8 sf = *(const LAS bf16x8*)(sfs + (16 * dvt + fr) * 72 + 32 * ks + 8 * fq);
;                 const bf16x8 sb = *(const LAS bf16x8*)(sbs + (16 * dvt + fr) * 72 + 32 * ks + 8 * fq);
;                 o = __builtin_amdgcn_mfma_f32_16x16x32_bf16(qF[ks], sf, o, 0, 0, 0);
;                 o = __builtin_amdgcn_mfma_f32_16x16x32_bf16(qB[ks], sb, o, 0, 0, 0);
;             }
;             O[dvt] = o;
;             __builtin_amdgcn_sched_barrier(0);
;         }
	v_cndmask_b32_e64 v68, 0, v183, s[74:75]
	v_fmac_f32_e32 v68, v66, v103
	v_exp_f32_e32 v66, v68
	v_ldexp_f32 v75, v72, v73
	v_cndmask_b32_e64 v68, 0, v184, s[74:75]
	v_pk_mul_f32 v[70:71], v[70:71], v[74:75]
	v_ldexp_f32 v74, v66, v68
	v_mul_f32_e32 v66, v67, v105
	v_cmp_gt_f32_e64 s[74:75], s3, v66
	v_lshlrev_b32_e32 v68, 16, v46
	v_cvt_pk_bf16_f32 v65, v70, v71
	v_cndmask_b32_e64 v66, 0, v183, s[74:75]
	v_fmac_f32_e32 v66, v67, v105
	v_exp_f32_e32 v66, v66
	v_cndmask_b32_e64 v67, 0, v184, s[74:75]
	v_ldexp_f32 v76, v66, v67
	v_pk_mul_f32 v[66:67], v[74:75], v[68:69] op_sel_hi:[0,1]
	v_pk_mul_f32 v[68:69], v[76:77], v[68:69] op_sel_hi:[0,1]
	v_cvt_pk_bf16_f32 v46, v68, v69
	v_lshlrev_b32_e32 v68, 16, v47
	v_and_b32_e32 v69, 0xffff0000, v47
	v_pk_mul_f32 v[70:71], v[74:75], v[68:69] op_sel_hi:[0,1]
	v_cvt_pk_bf16_f32 v66, v66, v67
	v_cvt_pk_bf16_f32 v67, v70, v71
	v_pk_mul_f32 v[68:69], v[76:77], v[68:69] op_sel_hi:[0,1]
	v_lshlrev_b32_e32 v70, 16, v48
	v_and_b32_e32 v71, 0xffff0000, v48
	v_cvt_pk_bf16_f32 v47, v68, v69
	v_pk_mul_f32 v[68:69], v[74:75], v[70:71] op_sel_hi:[0,1]
	v_pk_mul_f32 v[70:71], v[76:77], v[70:71] op_sel_hi:[0,1]
	v_cvt_pk_bf16_f32 v48, v70, v71
	v_lshlrev_b32_e32 v70, 16, v49
	v_and_b32_e32 v71, 0xffff0000, v49
	v_pk_mul_f32 v[72:73], v[74:75], v[70:71] op_sel_hi:[0,1]
	v_cvt_pk_bf16_f32 v68, v68, v69
	v_cvt_pk_bf16_f32 v69, v72, v73
	v_pk_mul_f32 v[70:71], v[76:77], v[70:71] op_sel_hi:[0,1]
	v_lshlrev_b32_e32 v72, 16, v42
	v_and_b32_e32 v73, 0xffff0000, v42
	v_cvt_pk_bf16_f32 v49, v70, v71
	v_pk_mul_f32 v[70:71], v[74:75], v[72:73] op_sel_hi:[0,1]
	v_pk_mul_f32 v[72:73], v[76:77], v[72:73] op_sel_hi:[0,1]
	v_cvt_pk_bf16_f32 v42, v72, v73
	v_lshlrev_b32_e32 v72, 16, v43
	v_and_b32_e32 v73, 0xffff0000, v43
	v_pk_mul_f32 v[78:79], v[74:75], v[72:73] op_sel_hi:[0,1]
	v_cvt_pk_bf16_f32 v70, v70, v71
	v_cvt_pk_bf16_f32 v71, v78, v79
	v_pk_mul_f32 v[72:73], v[76:77], v[72:73] op_sel_hi:[0,1]
	v_lshlrev_b32_e32 v78, 16, v44
	v_and_b32_e32 v79, 0xffff0000, v44
	v_cvt_pk_bf16_f32 v43, v72, v73
	v_pk_mul_f32 v[72:73], v[74:75], v[78:79] op_sel_hi:[0,1]
	v_pk_mul_f32 v[78:79], v[76:77], v[78:79] op_sel_hi:[0,1]
	v_cvt_pk_bf16_f32 v44, v78, v79
	v_lshlrev_b32_e32 v78, 16, v45
	v_and_b32_e32 v79, 0xffff0000, v45
	v_pk_mul_f32 v[74:75], v[74:75], v[78:79] op_sel_hi:[0,1]
	v_cvt_pk_bf16_f32 v72, v72, v73
	v_cvt_pk_bf16_f32 v73, v74, v75
	v_pk_mul_f32 v[74:75], v[76:77], v[78:79] op_sel_hi:[0,1]
	v_cvt_pk_bf16_f32 v45, v74, v75
	ds_read2_b64 v[74:77], v82 offset1:4
	ds_read2_b64 v[78:81], v82 offset0:8 offset1:12
	s_waitcnt lgkmcnt(1)
	v_mfma_f32_16x16x32_bf16 v[74:77], v[50:53], v[74:77], 0
	s_waitcnt lgkmcnt(0)
	v_mfma_f32_16x16x32_bf16 v[74:77], v[54:57], v[78:81], v[74:77]
	ds_read2_b64 v[78:81], v82 offset0:16 offset1:20
	s_waitcnt lgkmcnt(0)
	v_mfma_f32_16x16x32_bf16 v[74:77], v[58:61], v[78:81], v[74:77]
	ds_read2_b64 v[78:81], v82 offset0:24 offset1:28
	s_waitcnt lgkmcnt(0)
	v_mfma_f32_16x16x32_bf16 v[74:77], v[62:65], v[78:81], v[74:77]
	ds_read_b128 v[78:81], v231 offset:53248
	ds_read_b128 v[82:85], v232
	s_waitcnt lgkmcnt(1)
	v_mfma_f32_16x16x32_bf16 v[74:77], v[66:69], v[78:81], v[74:77]
	s_waitcnt lgkmcnt(0)
	v_mfma_f32_16x16x32_bf16 v[74:77], v[46:49], v[82:85], v[74:77]
	ds_read_b128 v[78:81], v231 offset:53312
	ds_read_b128 v[82:85], v232 offset:64
	s_waitcnt lgkmcnt(1)
	v_mfma_f32_16x16x32_bf16 v[74:77], v[70:73], v[78:81], v[74:77]
	s_waitcnt lgkmcnt(0)
	v_mfma_f32_16x16x32_bf16 v[74:77], v[42:45], v[82:85], v[74:77]
	v_add_u32_e32 v78, 0x1100, v230
	v_add_u32_e32 v86, 0x4800, v78
	ds_read2_b64 v[78:81], v86 offset1:4
	ds_read2_b64 v[82:85], v86 offset0:8 offset1:12
	s_waitcnt lgkmcnt(1)
	v_mfma_f32_16x16x32_bf16 v[78:81], v[50:53], v[78:81], 0
	s_waitcnt lgkmcnt(0)
	v_mfma_f32_16x16x32_bf16 v[78:81], v[54:57], v[82:85], v[78:81]
	ds_read2_b64 v[82:85], v86 offset0:16 offset1:20
	s_waitcnt lgkmcnt(0)
	v_mfma_f32_16x16x32_bf16 v[78:81], v[58:61], v[82:85], v[78:81]
	ds_read2_b64 v[82:85], v86 offset0:24 offset1:28
	s_waitcnt lgkmcnt(0)
	v_mfma_f32_16x16x32_bf16 v[78:81], v[62:65], v[82:85], v[78:81]
	ds_read_b128 v[82:85], v231 offset:55552
	s_waitcnt lgkmcnt(0)
	v_mfma_f32_16x16x32_bf16 v[78:81], v[66:69], v[82:85], v[78:81]
	ds_read_b128 v[82:85], v233
	s_waitcnt lgkmcnt(0)
	v_mfma_f32_16x16x32_bf16 v[78:81], v[46:49], v[82:85], v[78:81]
	ds_read_b128 v[82:85], v231 offset:55616
	s_waitcnt lgkmcnt(0)
	v_mfma_f32_16x16x32_bf16 v[78:81], v[70:73], v[82:85], v[78:81]
	ds_read_b128 v[82:85], v233 offset:64
	s_waitcnt lgkmcnt(0)
	v_mfma_f32_16x16x32_bf16 v[78:81], v[42:45], v[82:85], v[78:81]
	v_add_u32_e32 v82, 0x2200, v230
	v_add_u32_e32 v90, 0x4800, v82
	ds_read2_b64 v[82:85], v90 offset1:4
	ds_read2_b64 v[86:89], v90 offset0:8 offset1:12
	s_waitcnt lgkmcnt(1)
	v_mfma_f32_16x16x32_bf16 v[82:85], v[50:53], v[82:85], 0
	s_waitcnt lgkmcnt(0)
	v_mfma_f32_16x16x32_bf16 v[82:85], v[54:57], v[86:89], v[82:85]
	ds_read2_b64 v[86:89], v90 offset0:16 offset1:20
	s_waitcnt lgkmcnt(0)
	v_mfma_f32_16x16x32_bf16 v[82:85], v[58:61], v[86:89], v[82:85]
	ds_read2_b64 v[86:89], v90 offset0:24 offset1:28
	s_waitcnt lgkmcnt(0)
	v_mfma_f32_16x16x32_bf16 v[82:85], v[62:65], v[86:89], v[82:85]
	ds_read_b128 v[86:89], v231 offset:57856
	s_waitcnt lgkmcnt(0)
	v_mfma_f32_16x16x32_bf16 v[82:85], v[66:69], v[86:89], v[82:85]
	ds_read_b128 v[86:89], v234
	s_waitcnt lgkmcnt(0)
	v_mfma_f32_16x16x32_bf16 v[82:85], v[46:49], v[86:89], v[82:85]
	ds_read_b128 v[86:89], v231 offset:57920
	s_waitcnt lgkmcnt(0)
	v_mfma_f32_16x16x32_bf16 v[82:85], v[70:73], v[86:89], v[82:85]
	ds_read_b128 v[86:89], v234 offset:64
	s_waitcnt lgkmcnt(0)
; #define LAS __attribute__((address_space(3)))
; __device__ __forceinline__ void ret_out_phase(const Args& A, Frame& F, int l, bool lastl, bf16_t* ARET, bf16_t* ALRU) {
;     ...
;         f32x4 O[8];
; #pragma unroll
;         for (int dvt = 0; dvt < 8; ++dvt) {
;             f32x4 o = (f32x4){0.f, 0.f, 0.f, 0.f};
; #pragma unroll
;             for (int jp = 0; jp < 4; ++jp) {
;                 const u32x2 lo = *(const LAS u32x2*)(vts + (16 * dvt + fr) * 136 + 32 * jp + 4 * fq);
;                 const u32x2 hi = *(const LAS u32x2*)(vts + (16 * dvt + fr) * 136 + 32 * jp + 16 + 4 * fq);
;                 u32x4 bv; bv[0] = lo.x; bv[1] = lo.y; bv[2] = hi.x; bv[3] = hi.y;
;                 o = __builtin_amdgcn_mfma_f32_16x16x32_bf16(pa[jp], __builtin_bit_cast(bf16x8, bv), o, 0, 0, 0);
;             }
; #pragma unroll
;             for (int ks = 0; ks < 2; ++ks) {
;                 const bf16x8 sf = *(const LAS bf16x8*)(sfs + (16 * dvt + fr) * 72 + 32 * ks + 8 * fq);
;                 const bf16x8 sb = *(const LAS bf16x8*)(sbs + (16 * dvt + fr) * 72 + 32 * ks + 8 * fq);
;                 o = __builtin_amdgcn_mfma_f32_16x16x32_bf16(qF[ks], sf, o, 0, 0, 0);
;                 o = __builtin_amdgcn_mfma_f32_16x16x32_bf16(qB[ks], sb, o, 0, 0, 0);
;             }
;             O[dvt] = o;
;             __builtin_amdgcn_sched_barrier(0);
;         }
	v_mfma_f32_16x16x32_bf16 v[82:85], v[42:45], v[86:89], v[82:85]
	v_add_u32_e32 v86, 0x3300, v230
	v_add_u32_e32 v94, 0x4800, v86
	ds_read2_b64 v[86:89], v94 offset1:4
	ds_read2_b64 v[90:93], v94 offset0:8 offset1:12
	s_waitcnt lgkmcnt(1)
	v_mfma_f32_16x16x32_bf16 v[86:89], v[50:53], v[86:89], 0
	s_waitcnt lgkmcnt(0)
	v_mfma_f32_16x16x32_bf16 v[86:89], v[54:57], v[90:93], v[86:89]
	ds_read2_b64 v[90:93], v94 offset0:16 offset1:20
	s_waitcnt lgkmcnt(0)
	v_mfma_f32_16x16x32_bf16 v[86:89], v[58:61], v[90:93], v[86:89]
	ds_read2_b64 v[90:93], v94 offset0:24 offset1:28
	s_waitcnt lgkmcnt(0)
	v_mfma_f32_16x16x32_bf16 v[86:89], v[62:65], v[90:93], v[86:89]
	ds_read_b128 v[90:93], v160 offset:55552
	s_waitcnt lgkmcnt(0)
	v_mfma_f32_16x16x32_bf16 v[86:89], v[66:69], v[90:93], v[86:89]
	ds_read_b128 v[90:93], v235
	s_waitcnt lgkmcnt(0)
	v_mfma_f32_16x16x32_bf16 v[86:89], v[46:49], v[90:93], v[86:89]
	ds_read_b128 v[90:93], v160 offset:55616
	s_waitcnt lgkmcnt(0)
	v_mfma_f32_16x16x32_bf16 v[86:89], v[70:73], v[90:93], v[86:89]
	ds_read_b128 v[90:93], v235 offset:64
	s_waitcnt lgkmcnt(0)
	v_mfma_f32_16x16x32_bf16 v[86:89], v[42:45], v[90:93], v[86:89]
	v_add_u32_e32 v90, 0x4400, v230
	v_add_u32_e32 v98, 0x4800, v90
	ds_read2_b64 v[90:93], v98 offset1:4
	ds_read2_b64 v[94:97], v98 offset0:8 offset1:12
	s_waitcnt lgkmcnt(1)
	v_mfma_f32_16x16x32_bf16 v[90:93], v[50:53], v[90:93], 0
	s_waitcnt lgkmcnt(0)
	v_mfma_f32_16x16x32_bf16 v[90:93], v[54:57], v[94:97], v[90:93]
	ds_read2_b64 v[94:97], v98 offset0:16 offset1:20
	s_waitcnt lgkmcnt(0)
	v_mfma_f32_16x16x32_bf16 v[90:93], v[58:61], v[94:97], v[90:93]
	ds_read2_b64 v[94:97], v98 offset0:24 offset1:28
	s_waitcnt lgkmcnt(0)
	v_mfma_f32_16x16x32_bf16 v[90:93], v[62:65], v[94:97], v[90:93]
	ds_read_b128 v[94:97], v236 offset:53248
	s_waitcnt lgkmcnt(0)
	v_mfma_f32_16x16x32_bf16 v[90:93], v[66:69], v[94:97], v[90:93]
	ds_read_b128 v[94:97], v237
	s_waitcnt lgkmcnt(0)
	v_mfma_f32_16x16x32_bf16 v[90:93], v[46:49], v[94:97], v[90:93]
	ds_read_b128 v[94:97], v236 offset:53312
	s_waitcnt lgkmcnt(0)
	v_mfma_f32_16x16x32_bf16 v[90:93], v[70:73], v[94:97], v[90:93]
	ds_read_b128 v[94:97], v237 offset:64
	s_waitcnt lgkmcnt(0)
	v_mfma_f32_16x16x32_bf16 v[90:93], v[42:45], v[94:97], v[90:93]
	v_add_u32_e32 v94, 0x5500, v230
	v_add_u32_e32 v129, 0x4800, v94
	ds_read2_b64 v[94:97], v129 offset1:4
	ds_read2_b64 v[98:101], v129 offset0:8 offset1:12
	s_waitcnt lgkmcnt(1)
	v_mfma_f32_16x16x32_bf16 v[94:97], v[50:53], v[94:97], 0
	s_waitcnt lgkmcnt(0)
	v_mfma_f32_16x16x32_bf16 v[94:97], v[54:57], v[98:101], v[94:97]
	ds_read2_b64 v[98:101], v129 offset0:16 offset1:20
	s_waitcnt lgkmcnt(0)
	v_mfma_f32_16x16x32_bf16 v[94:97], v[58:61], v[98:101], v[94:97]
	ds_read2_b64 v[98:101], v129 offset0:24 offset1:28
	s_waitcnt lgkmcnt(0)
	v_mfma_f32_16x16x32_bf16 v[94:97], v[62:65], v[98:101], v[94:97]
	ds_read_b128 v[98:101], v238 offset:53248
	s_waitcnt lgkmcnt(0)
	v_mfma_f32_16x16x32_bf16 v[94:97], v[66:69], v[98:101], v[94:97]
	ds_read_b128 v[98:101], v239
	s_waitcnt lgkmcnt(0)
	v_mfma_f32_16x16x32_bf16 v[94:97], v[46:49], v[98:101], v[94:97]
	ds_read_b128 v[98:101], v238 offset:53312
	s_waitcnt lgkmcnt(0)
	v_mfma_f32_16x16x32_bf16 v[94:97], v[70:73], v[98:101], v[94:97]
	ds_read_b128 v[98:101], v239 offset:64
	s_waitcnt lgkmcnt(0)
	v_mfma_f32_16x16x32_bf16 v[94:97], v[42:45], v[98:101], v[94:97]
	v_add_u32_e32 v98, 0x6600, v230
	v_add_u32_e32 v129, 0x4800, v98
	ds_read2_b64 v[98:101], v129 offset1:4
	ds_read2_b64 v[250:253], v129 offset0:8 offset1:12
	s_waitcnt lgkmcnt(1)
	v_mfma_f32_16x16x32_bf16 v[98:101], v[50:53], v[98:101], 0
	s_waitcnt lgkmcnt(0)
	v_mfma_f32_16x16x32_bf16 v[98:101], v[54:57], v[250:253], v[98:101]
	ds_read2_b64 v[250:253], v129 offset0:16 offset1:20
	s_waitcnt lgkmcnt(0)
	v_mfma_f32_16x16x32_bf16 v[98:101], v[58:61], v[250:253], v[98:101]
	ds_read2_b64 v[250:253], v129 offset0:24 offset1:28
	s_waitcnt lgkmcnt(0)
	v_mfma_f32_16x16x32_bf16 v[98:101], v[62:65], v[250:253], v[98:101]
	ds_read_b128 v[250:253], v240 offset:53248
	s_waitcnt lgkmcnt(0)
	v_mfma_f32_16x16x32_bf16 v[98:101], v[66:69], v[250:253], v[98:101]
	ds_read_b128 v[250:253], v241
	s_waitcnt lgkmcnt(0)
	v_mfma_f32_16x16x32_bf16 v[98:101], v[46:49], v[250:253], v[98:101]
	ds_read_b128 v[250:253], v240 offset:53312
	s_waitcnt lgkmcnt(0)
	v_mfma_f32_16x16x32_bf16 v[98:101], v[70:73], v[250:253], v[98:101]
	ds_read_b128 v[250:253], v241 offset:64
	s_waitcnt lgkmcnt(0)
	v_mfma_f32_16x16x32_bf16 v[98:101], v[42:45], v[250:253], v[98:101]
	v_add_u32_e32 v129, 0x4800, v242
	ds_read2_b64 v[250:253], v129 offset1:4
	s_waitcnt lgkmcnt(0)
	v_mfma_f32_16x16x32_bf16 v[50:53], v[50:53], v[250:253], 0
	ds_read2_b64 v[250:253], v129 offset0:8 offset1:12
	s_waitcnt lgkmcnt(0)
	v_mfma_f32_16x16x32_bf16 v[50:53], v[54:57], v[250:253], v[50:53]
	ds_read2_b64 v[54:57], v129 offset0:16 offset1:20
	s_waitcnt lgkmcnt(0)
	v_mfma_f32_16x16x32_bf16 v[50:53], v[58:61], v[54:57], v[50:53]
	ds_read2_b64 v[54:57], v129 offset0:24 offset1:28
	s_waitcnt lgkmcnt(0)
	v_mfma_f32_16x16x32_bf16 v[50:53], v[62:65], v[54:57], v[50:53]
	ds_read_b128 v[54:57], v243 offset:53248
	ds_read_b128 v[58:61], v243 offset:53312
	s_waitcnt lgkmcnt(1)
	v_mfma_f32_16x16x32_bf16 v[50:53], v[66:69], v[54:57], v[50:53]
	ds_read_b128 v[54:57], v244
	ds_read_b128 v[62:65], v244 offset:64
	s_waitcnt lgkmcnt(1)
	v_mfma_f32_16x16x32_bf16 v[46:49], v[46:49], v[54:57], v[50:53]
	v_mfma_f32_16x16x32_bf16 v[46:49], v[70:73], v[58:61], v[46:49]
	s_waitcnt lgkmcnt(0)
; __device__ __forceinline__ bf16_t f2bf(float f) { return (bf16_t)(pk2(f, 0.f) & 0xffffu); }
; __device__ __forceinline__ void ret_out_phase(const Args& A, Frame& F, int l, bool lastl, bf16_t* ARET, bf16_t* ALRU) {
;     ...
; #pragma unroll
;         for (int r = 0; r < 4; ++r) {
;             float sm = 0.f;
; #pragma unroll
;             for (int dvt = 0; dvt < 8; ++dvt) sm += O[dvt][r];
;             const float mu = sum16(sm) * (1.f / DV);
;             float q2 = 0.f;
; #pragma unroll
;             for (int dvt = 0; dvt < 8; ++dvt) { const float dd = O[dvt][r] - mu; q2 += dd * dd; }
;             const float rstd = rsqrtf(sum16(q2) * (1.f / DV) + EPS);
; #pragma unroll
;             for (int dvt = 0; dvt < 8; ++dvt) os[(16 * w + 4 * fq + r) * 136 + 16 * dvt + fr] = f2bf((O[dvt][r] - mu) * rstd);
;         }
	v_mfma_f32_16x16x32_bf16 v[42:45], v[42:45], v[62:65], v[46:49]
	s_nop 5
	v_add_f32_e64 v46, v74, 0
	v_add_f32_e64 v47, v75, 0
	v_mov_b32_e32 v50, v86
	v_pk_add_f32 v[46:47], v[46:47], v[78:79]
	v_mov_b32_e32 v51, v82
	v_pk_add_f32 v[46:47], v[46:47], v[82:83]
	v_mov_b32_e32 v82, v87
	v_pk_add_f32 v[46:47], v[46:47], v[86:87]
	v_mov_b32_e32 v52, v94
	v_pk_add_f32 v[46:47], v[46:47], v[90:91]
	v_mov_b32_e32 v53, v90
	v_pk_add_f32 v[46:47], v[46:47], v[94:95]
	v_mov_b32_e32 v90, v95
	v_pk_add_f32 v[46:47], v[46:47], v[98:99]
	v_mov_b32_e32 v54, v42
	v_pk_add_f32 v[46:47], v[46:47], v[42:43]
	v_mov_b32_e32 v55, v98
	v_mov_b32_e32 v98, v43
	s_mov_b32 s2, 0x358637bd
	s_add_i32 vcc_hi, vcc_hi, s34
	s_waitcnt lgkmcnt(0)
	s_nop 1
	v_add_f32_dpp v46, v46, v46 quad_perm:[1,0,3,2] row_mask:0xf bank_mask:0xf
	v_add_f32_dpp v47, v47, v47 quad_perm:[1,0,3,2] row_mask:0xf bank_mask:0xf
	s_add_i32 s61, s61, s60
	s_cmp_lg_u32 s37, s39
	s_waitcnt lgkmcnt(0)
	s_nop 1
	v_add_f32_dpp v46, v46, v46 quad_perm:[2,3,0,1] row_mask:0xf bank_mask:0xf
	v_add_f32_dpp v47, v47, v47 quad_perm:[2,3,0,1] row_mask:0xf bank_mask:0xf
	s_waitcnt lgkmcnt(0)
	s_nop 1
	v_add_f32_dpp v46, v46, v46 row_half_mirror row_mask:0xf bank_mask:0xf
	v_add_f32_dpp v47, v47, v47 row_half_mirror row_mask:0xf bank_mask:0xf
	s_waitcnt lgkmcnt(0)
	s_nop 1
	v_add_f32_dpp v46, v46, v46 row_mirror row_mask:0xf bank_mask:0xf
	v_add_f32_dpp v47, v47, v47 row_mirror row_mask:0xf bank_mask:0xf
	s_nop 0
	v_pk_mul_f32 v[48:49], v[46:47], s[18:19] op_sel_hi:[1,0]
	v_pk_fma_f32 v[64:65], v[46:47], s[18:19], v[78:79] op_sel_hi:[1,0,1] neg_lo:[1,0,0] neg_hi:[1,0,0]
	v_pk_add_f32 v[50:51], v[50:51], v[48:49] op_sel_hi:[1,0] neg_lo:[0,1] neg_hi:[0,1]
	v_pk_add_f32 v[68:69], v[82:83], v[48:49] op_sel:[0,1] neg_lo:[0,1] neg_hi:[0,1]
	v_pk_fma_f32 v[56:57], v[46:47], s[18:19], v[74:75] op_sel_hi:[1,0,1] neg_lo:[1,0,0] neg_hi:[1,0,0]
	v_pk_mul_f32 v[58:59], v[50:51], v[50:51]
	v_pk_mul_f32 v[46:47], v[64:65], v[64:65]
	v_pk_mul_f32 v[70:71], v[68:69], v[68:69]
	v_pk_add_f32 v[52:53], v[52:53], v[48:49] op_sel_hi:[1,0] neg_lo:[0,1] neg_hi:[0,1]
	v_pk_fma_f32 v[66:67], v[56:57], v[56:57], v[46:47]
	v_pk_add_f32 v[46:47], v[90:91], v[48:49] op_sel:[0,1] neg_lo:[0,1] neg_hi:[0,1]
	v_mov_b32_e32 v75, v58
	v_mov_b32_e32 v58, v71
	v_pk_mul_f32 v[60:61], v[52:53], v[52:53]
	v_pk_mul_f32 v[72:73], v[46:47], v[46:47]
	v_mov_b32_e32 v74, v70
	v_pk_add_f32 v[58:59], v[58:59], v[66:67] op_sel:[0,1] op_sel_hi:[1,0]
	v_pk_add_f32 v[54:55], v[54:55], v[48:49] op_sel_hi:[1,0] neg_lo:[0,1] neg_hi:[0,1]
	v_pk_add_f32 v[42:43], v[98:99], v[48:49] op_sel:[0,1] neg_lo:[0,1] neg_hi:[0,1]
	v_pk_add_f32 v[58:59], v[74:75], v[58:59]
	v_mov_b32_e32 v66, v73
	v_mov_b32_e32 v67, v61
	v_pk_mul_f32 v[62:63], v[54:55], v[54:55]
	v_pk_mul_f32 v[48:49], v[42:43], v[42:43]
	v_pk_add_f32 v[58:59], v[66:67], v[58:59]
	v_mov_b32_e32 v73, v60
	v_pk_add_f32 v[58:59], v[72:73], v[58:59]
	v_mov_b32_e32 v60, v49
	v_mov_b32_e32 v61, v63
	v_pk_add_f32 v[58:59], v[60:61], v[58:59]
	v_mov_b32_e32 v49, v62
	v_pk_add_f32 v[48:49], v[48:49], v[58:59]
	s_waitcnt lgkmcnt(0)
	s_nop 1
	v_add_f32_dpp v48, v48, v48 quad_perm:[1,0,3,2] row_mask:0xf bank_mask:0xf
	v_add_f32_dpp v49, v49, v49 quad_perm:[1,0,3,2] row_mask:0xf bank_mask:0xf
	s_waitcnt lgkmcnt(0)
	s_nop 1
	v_add_f32_dpp v48, v48, v48 quad_perm:[2,3,0,1] row_mask:0xf bank_mask:0xf
	v_add_f32_dpp v49, v49, v49 quad_perm:[2,3,0,1] row_mask:0xf bank_mask:0xf
	s_waitcnt lgkmcnt(0)
	s_nop 1
	v_add_f32_dpp v48, v48, v48 row_half_mirror row_mask:0xf bank_mask:0xf
	v_add_f32_dpp v49, v49, v49 row_half_mirror row_mask:0xf bank_mask:0xf
	s_waitcnt lgkmcnt(0)
	s_nop 1
	v_add_f32_dpp v48, v48, v48 row_mirror row_mask:0xf bank_mask:0xf
	v_add_f32_dpp v49, v49, v49 row_mirror row_mask:0xf bank_mask:0xf
	v_mov_b64_e32 v[58:59], s[2:3]
	v_pk_fma_f32 v[48:49], v[48:49], s[18:19], v[58:59] op_sel_hi:[1,0,0]
	s_mov_b32 s2, 0xfcc8000
	v_mul_f32_e32 v60, 0x4b800000, v49
	v_cmp_gt_f32_e64 s[74:75], s33, v49
	s_nop 1
	v_cndmask_b32_e64 v49, v49, v60, s[74:75]
	v_rsq_f32_e32 v49, v49
	s_nop 0
	v_mul_f32_e32 v60, 0x45800000, v49
	v_cndmask_b32_e64 v49, v49, v60, s[74:75]
	v_mul_f32_e32 v50, v50, v49
	v_cvt_pk_bf16_f32 v50, v50, s0
	ds_write_b16 v249, v50 offset:96
	v_mul_f32_e32 v50, v53, v49
	v_cvt_pk_bf16_f32 v50, v50, s0
	v_mul_f32_e32 v56, v56, v49
	ds_write_b16 v249, v50 offset:128
	v_mul_f32_e32 v50, v52, v49
	v_cvt_pk_bf16_f32 v56, v56, s0
	v_cvt_pk_bf16_f32 v50, v50, s0
	ds_write_b16 v249, v56
	v_mul_f32_e32 v56, v64, v49
	v_mul_f32_e32 v51, v51, v49
	ds_write_b16 v249, v50 offset:160
	v_mul_f32_e32 v50, v55, v49
	v_mul_f32_e32 v52, v54, v49
	v_mul_f32_e32 v49, 0x4b800000, v48
	v_cmp_gt_f32_e64 s[74:75], s33, v48
	v_cvt_pk_bf16_f32 v51, v51, s0
	v_cvt_pk_bf16_f32 v50, v50, s0
	v_cndmask_b32_e64 v48, v48, v49, s[74:75]
	v_rsq_f32_e32 v53, v48
	v_pk_add_f32 v[48:49], v[76:77], 0 op_sel_hi:[1,0]
	ds_write_b16 v249, v51 offset:64
	v_pk_add_f32 v[48:49], v[48:49], v[80:81]
	ds_write_b16 v249, v50 offset:192
	v_pk_add_f32 v[48:49], v[48:49], v[84:85]
	v_cvt_pk_bf16_f32 v52, v52, s0
	v_pk_add_f32 v[48:49], v[48:49], v[88:89]
	ds_write_b16 v249, v52 offset:224
	v_pk_add_f32 v[48:49], v[48:49], v[92:93]
	v_mul_f32_e32 v52, 0x45800000, v53
	v_pk_add_f32 v[48:49], v[48:49], v[96:97]
	v_cndmask_b32_e64 v82, v53, v52, s[74:75]
	v_pk_add_f32 v[48:49], v[48:49], v[100:101]
	v_mul_f32_e32 v52, v57, v82
	v_pk_add_f32 v[48:49], v[48:49], v[44:45]
	v_cvt_pk_bf16_f32 v52, v52, s0
	ds_write_b16 v249, v52 offset:272
	v_mul_f32_e32 v52, v65, v82
	v_cvt_pk_bf16_f32 v83, v52, s0
	s_waitcnt lgkmcnt(1)
; __device__ __forceinline__ bf16_t f2bf(float f) { return (bf16_t)(pk2(f, 0.f) & 0xffffu); }
; __device__ __forceinline__ void ret_out_phase(const Args& A, Frame& F, int l, bool lastl, bf16_t* ARET, bf16_t* ALRU) {
;     ...
; #pragma unroll
;         for (int r = 0; r < 4; ++r) {
;             float sm = 0.f;
; #pragma unroll
;             for (int dvt = 0; dvt < 8; ++dvt) sm += O[dvt][r];
;             const float mu = sum16(sm) * (1.f / DV);
;             float q2 = 0.f;
; #pragma unroll
;             for (int dvt = 0; dvt < 8; ++dvt) { const float dd = O[dvt][r] - mu; q2 += dd * dd; }
;             const float rstd = rsqrtf(sum16(q2) * (1.f / DV) + EPS);
; #pragma unroll
;             for (int dvt = 0; dvt < 8; ++dvt) os[(16 * w + 4 * fq + r) * 136 + 16 * dvt + fr] = f2bf((O[dvt][r] - mu) * rstd);
;         }
;         __builtin_amdgcn_fence(__ATOMIC_RELEASE, "workgroup"); __builtin_amdgcn_wave_barrier(); __builtin_amdgcn_fence(__ATOMIC_ACQUIRE, "workgroup");
;         {
;             const int rr = 16 * w + (lane >> 2), cc = (lane & 3) * 32;
;             const size_t go = (rowbase + rr) * D + 128 * h + cc;
	s_nop 1
	v_add_f32_dpp v48, v48, v48 quad_perm:[1,0,3,2] row_mask:0xf bank_mask:0xf
	v_add_f32_dpp v49, v49, v49 quad_perm:[1,0,3,2] row_mask:0xf bank_mask:0xf
	v_mov_b32_e32 v52, v88
	v_mov_b32_e32 v53, v84
	v_mov_b32_e32 v84, v89
	v_mov_b32_e32 v54, v96
	s_waitcnt lgkmcnt(0)
	s_nop 1
	v_add_f32_dpp v48, v48, v48 quad_perm:[2,3,0,1] row_mask:0xf bank_mask:0xf
	v_add_f32_dpp v49, v49, v49 quad_perm:[2,3,0,1] row_mask:0xf bank_mask:0xf
	v_mov_b32_e32 v55, v92
	v_mov_b32_e32 v92, v97
	v_cvt_pk_bf16_f32 v56, v56, s0
	ds_write_b16 v249, v56 offset:32
	s_waitcnt lgkmcnt(1)
	s_nop 1
	v_add_f32_dpp v48, v48, v48 row_half_mirror row_mask:0xf bank_mask:0xf
	v_add_f32_dpp v49, v49, v49 row_half_mirror row_mask:0xf bank_mask:0xf
	v_mov_b32_e32 v56, v44
	v_mov_b32_e32 v57, v100
	v_mov_b32_e32 v100, v45
	v_mul_f32_e32 v47, v47, v82
	s_waitcnt lgkmcnt(0)
	s_nop 1
	v_add_f32_dpp v48, v48, v48 row_mirror row_mask:0xf bank_mask:0xf
	v_add_f32_dpp v49, v49, v49 row_mirror row_mask:0xf bank_mask:0xf
	v_cvt_pk_bf16_f32 v47, v47, s0
	v_pk_mul_f32 v[50:51], v[48:49], s[18:19] op_sel_hi:[1,0]
	v_pk_fma_f32 v[66:67], v[48:49], s[18:19], v[76:77] op_sel_hi:[1,0,1] neg_lo:[1,0,0] neg_hi:[1,0,0]
	v_pk_add_f32 v[52:53], v[52:53], v[50:51] op_sel_hi:[1,0] neg_lo:[0,1] neg_hi:[0,1]
	v_pk_fma_f32 v[48:49], v[48:49], s[18:19], v[80:81] op_sel_hi:[1,0,1] neg_lo:[1,0,0] neg_hi:[1,0,0]
	v_pk_add_f32 v[72:73], v[84:85], v[50:51] op_sel:[0,1] neg_lo:[0,1] neg_hi:[0,1]
	v_pk_mul_f32 v[60:61], v[52:53], v[52:53]
	v_pk_mul_f32 v[70:71], v[48:49], v[48:49]
	v_pk_mul_f32 v[74:75], v[72:73], v[72:73]
	v_pk_add_f32 v[54:55], v[54:55], v[50:51] op_sel_hi:[1,0] neg_lo:[0,1] neg_hi:[0,1]
	v_pk_fma_f32 v[70:71], v[66:67], v[66:67], v[70:71]
	v_pk_add_f32 v[76:77], v[92:93], v[50:51] op_sel:[0,1] neg_lo:[0,1] neg_hi:[0,1]
	v_mov_b32_e32 v81, v60
	v_mov_b32_e32 v60, v75
	v_pk_mul_f32 v[62:63], v[54:55], v[54:55]
	v_pk_mul_f32 v[78:79], v[76:77], v[76:77]
	v_mov_b32_e32 v80, v74
	v_pk_add_f32 v[60:61], v[60:61], v[70:71] op_sel:[0,1] op_sel_hi:[1,0]
	v_pk_add_f32 v[56:57], v[56:57], v[50:51] op_sel_hi:[1,0] neg_lo:[0,1] neg_hi:[0,1]
	v_pk_add_f32 v[44:45], v[100:101], v[50:51] op_sel:[0,1] neg_lo:[0,1] neg_hi:[0,1]
	v_pk_add_f32 v[60:61], v[80:81], v[60:61]
	v_mov_b32_e32 v70, v79
	v_mov_b32_e32 v71, v63
	v_pk_mul_f32 v[64:65], v[56:57], v[56:57]
	v_pk_mul_f32 v[50:51], v[44:45], v[44:45]
	v_pk_add_f32 v[60:61], v[70:71], v[60:61]
	v_mov_b32_e32 v79, v62
	v_pk_add_f32 v[60:61], v[78:79], v[60:61]
	v_mov_b32_e32 v62, v51
	v_mov_b32_e32 v63, v65
	v_pk_add_f32 v[60:61], v[62:63], v[60:61]
	v_mov_b32_e32 v51, v64
	v_pk_add_f32 v[50:51], v[50:51], v[60:61]
	v_mul_f32_e32 v62, v69, v82
	v_cvt_pk_bf16_f32 v62, v62, s0
	ds_write_b16 v249, v62 offset:336
	v_mul_f32_e32 v62, v68, v82
	s_waitcnt lgkmcnt(1)
	s_nop 1
	v_add_f32_dpp v50, v50, v50 quad_perm:[1,0,3,2] row_mask:0xf bank_mask:0xf
	v_add_f32_dpp v51, v51, v51 quad_perm:[1,0,3,2] row_mask:0xf bank_mask:0xf
	v_cvt_pk_bf16_f32 v62, v62, s0
	v_mul_f32_e32 v46, v46, v82
	ds_write_b16 v249, v62 offset:368
	ds_write_b16 v249, v47 offset:400
	s_waitcnt lgkmcnt(2)
	s_nop 1
	v_add_f32_dpp v50, v50, v50 quad_perm:[2,3,0,1] row_mask:0xf bank_mask:0xf
	v_add_f32_dpp v51, v51, v51 quad_perm:[2,3,0,1] row_mask:0xf bank_mask:0xf
	v_cvt_pk_bf16_f32 v62, v46, s0
	v_mul_f32_e32 v43, v43, v82
	v_cvt_pk_bf16_f32 v43, v43, s0
	ds_write_b16 v249, v43 offset:464
	s_waitcnt lgkmcnt(1)
	s_nop 1
	v_add_f32_dpp v46, v50, v50 row_half_mirror row_mask:0xf bank_mask:0xf
	v_add_f32_dpp v47, v51, v51 row_half_mirror row_mask:0xf bank_mask:0xf
	v_mul_f32_e32 v42, v42, v82
	v_cvt_pk_bf16_f32 v42, v42, s0
	ds_write_b16 v249, v42 offset:496
	ds_write_b16 v249, v83 offset:304
	s_waitcnt lgkmcnt(2)
	s_nop 1
	v_add_f32_dpp v46, v46, v46 row_mirror row_mask:0xf bank_mask:0xf
	v_add_f32_dpp v47, v47, v47 row_mirror row_mask:0xf bank_mask:0xf
	ds_write_b16 v249, v62 offset:432
	v_pk_fma_f32 v[46:47], v[46:47], s[18:19], v[58:59] op_sel_hi:[1,0,0]
	s_nop 0
	v_mul_f32_e32 v43, 0x4b800000, v47
	v_cmp_gt_f32_e64 s[74:75], s33, v47
	s_nop 1
	v_cndmask_b32_e64 v43, v47, v43, s[74:75]
	v_rsq_f32_e32 v43, v43
	s_nop 0
	v_mul_f32_e32 v42, 0x45800000, v43
	v_cndmask_b32_e64 v42, v43, v42, s[74:75]
	v_mul_f32_e32 v43, v66, v42
	v_cvt_pk_bf16_f32 v43, v43, s0
	ds_write_b16 v249, v43 offset:544
	v_mul_f32_e32 v43, v48, v42
	v_cvt_pk_bf16_f32 v43, v43, s0
	ds_write_b16 v249, v43 offset:576
	v_mul_f32_e32 v43, v53, v42
	v_cvt_pk_bf16_f32 v43, v43, s0
	ds_write_b16 v249, v43 offset:608
	v_mul_f32_e32 v43, v52, v42
	v_cvt_pk_bf16_f32 v43, v43, s0
	ds_write_b16 v249, v43 offset:640
	v_mul_f32_e32 v43, v55, v42
	v_cvt_pk_bf16_f32 v43, v43, s0
	ds_write_b16 v249, v43 offset:672
	v_mul_f32_e32 v43, v54, v42
	v_cvt_pk_bf16_f32 v43, v43, s0
	ds_write_b16 v249, v43 offset:704
	v_mul_f32_e32 v43, v57, v42
	v_cvt_pk_bf16_f32 v43, v43, s0
	ds_write_b16 v249, v43 offset:736
	v_mul_f32_e32 v43, 0x4b800000, v46
	v_cmp_gt_f32_e64 s[74:75], s33, v46
	v_mul_f32_e32 v42, v56, v42
	v_cvt_pk_bf16_f32 v42, v42, s0
	v_cndmask_b32_e64 v43, v46, v43, s[74:75]
	v_rsq_f32_e32 v43, v43
	ds_write_b16 v249, v42 offset:768
	v_mul_f32_e32 v42, 0x45800000, v43
	v_cndmask_b32_e64 v42, v43, v42, s[74:75]
	v_mul_f32_e32 v43, v67, v42
	v_cvt_pk_bf16_f32 v43, v43, s0
	ds_write_b16 v249, v43 offset:816
	v_mul_f32_e32 v43, v49, v42
	v_cvt_pk_bf16_f32 v43, v43, s0
	ds_write_b16 v249, v43 offset:848
	v_mul_f32_e32 v43, v73, v42
	v_cvt_pk_bf16_f32 v43, v43, s0
	ds_write_b16 v249, v43 offset:880
	v_mul_f32_e32 v43, v72, v42
	v_cvt_pk_bf16_f32 v43, v43, s0
	ds_write_b16 v249, v43 offset:912
	v_mul_f32_e32 v43, v77, v42
	v_cvt_pk_bf16_f32 v43, v43, s0
	ds_write_b16 v249, v43 offset:944
	v_mul_f32_e32 v43, v76, v42
	v_cvt_pk_bf16_f32 v43, v43, s0
	ds_write_b16 v249, v43 offset:976
	v_mul_f32_e32 v43, v45, v42
	v_mul_f32_e32 v42, v44, v42
	v_cvt_pk_bf16_f32 v43, v43, s0
	v_cvt_pk_bf16_f32 v42, v42, s0
	ds_write_b16 v249, v43 offset:1008
	ds_write_b16 v249, v42 offset:1040
	v_lshl_add_u64 v[42:43], s[8:9], 0, v[124:125]
	v_lshlrev_b64 v[42:43], 10, v[42:43]
	v_or_b32_e32 v42, v42, v126
	v_or_b32_e32 v42, s82, v42
	v_lshlrev_b64 v[54:55], 1, v[42:43]
	v_lshl_add_u64 v[42:43], s[50:51], 0, v[54:55]
	s_waitcnt lgkmcnt(0)
; #define LAS __attribute__((address_space(3)))
; __device__ __forceinline__ unsigned pk2(float lo, float hi) { const f32x2_t v = {lo, hi}; const bf16v2_t b = __builtin_convertvector(v, bf16v2_t); return __builtin_bit_cast(unsigned, b); }
; __device__ __forceinline__ float bflo(unsigned u) { return __uint_as_float(u << 16); }
; __device__ __forceinline__ float bfhi(unsigned u) { return __uint_as_float(u & 0xffff0000u); }
; __device__ __forceinline__ void ret_out_phase(const Args& A, Frame& F, int l, bool lastl, bf16_t* ARET, bf16_t* ALRU) {
;     ...
;         {
;             const int rr = 16 * w + (lane >> 2), cc = (lane & 3) * 32;
;             const size_t go = (rowbase + rr) * D + 128 * h + cc;
; #pragma unroll
;             for (int i = 0; i < 4; ++i) {
;                 const u32x4 ov = *(const LAS u32x4*)(os + rr * 136 + cc + 8 * i);
;                 const u32x4 gv = *(const u32x4*)(WSB(WS_SG) + go + 8 * i);
;                 u32x4 rv;
; #pragma unroll
;                 for (int e = 0; e < 4; ++e) rv[e] = pk2(bflo(ov[e]) * bflo(gv[e]), bfhi(ov[e]) * bfhi(gv[e]));
;                 *(u32x4*)(ARET + go + 8 * i) = rv;
;             }
;         }
; #pragma unroll
;         for (int i = 0; i < 4; ++i) {
;             const int u = tid + i * NTHREADS, r = u >> 4, c8 = (u & 15) * 8;
;             const size_t o = (rowbase + r) * D + 128 * h + c8;
;             const u32x4 hf = *(const u32x4*)(WSB(WS_HF) + o), hb = *(const u32x4*)(WSB(WS_HB) + o), gg = *(const u32x4*)(WSB(WS_GG) + o);
	v_and_b32_e32 v131, 15, v124
	v_lshrrev_b32_e32 v132, 1, v131
	v_sub_u32_e32 v100, v131, v132
	v_and_b32_e32 v131, 1, v131
	v_lshrrev_b32_e32 v127, 5, v126
	v_lshl_or_b32 v131, v131, 2, v127
	v_sub_u32_e32 v129, v124, v100
	v_add_u32_e32 v129, s8, v129
	v_lshlrev_b32_e32 v129, 11, v129
	v_lshl_or_b32 v127, v131, 3, s82
	v_lshl_or_b32 v129, v127, 1, v129
	v_add_u32_e32 v127, 0x4000, v129
	v_mul_u32_u24_e32 v100, 0x110, v100
	v_sub_u32_e32 v130, v133, v100
	v_lshlrev_b32_e32 v100, 1, v126
	v_sub_u32_e32 v130, v130, v100
	v_lshl_add_u32 v130, v131, 4, v130
	v_or_b32_e32 v100, s82, v104
	v_add_u32_e32 v141, s8, v106
	v_lshlrev_b32_e32 v141, 11, v141
	v_lshl_or_b32 v141, v100, 1, v141
	v_add_u32_e32 v250, s8, v108
	v_lshlrev_b32_e32 v250, 11, v250
	v_lshl_or_b32 v250, v100, 1, v250
	v_add_u32_e32 v251, s8, v110
	v_lshlrev_b32_e32 v251, 11, v251
	v_lshl_or_b32 v251, v100, 1, v251
	v_add_u32_e32 v252, s8, v112
	v_lshlrev_b32_e32 v252, 11, v252
	v_lshl_or_b32 v252, v100, 1, v252
	global_load_dwordx4 v[56:59], v129, s[50:51]
	global_load_dwordx4 v[60:63], v127, s[50:51]
	global_load_dwordx4 v[64:67], v129, s[50:51] offset:128
	global_load_dwordx4 v[68:71], v127, s[50:51] offset:128
	global_load_dwordx4 v[72:75], v141, s[10:11]
	global_load_dwordx4 v[76:79], v141, s[12:13]
	global_load_dwordx4 v[80:83], v141, s[14:15]
	global_load_dwordx4 v[84:87], v250, s[10:11]
	global_load_dwordx4 v[88:91], v250, s[12:13]
	global_load_dwordx4 v[92:95], v250, s[14:15]
	ds_read_b128 v[96:99], v130
	ds_read_b128 v[44:47], v130 offset:2176
	s_waitcnt vmcnt(9) lgkmcnt(1)
	v_lshlrev_b32_e32 v100, 16, v96
	v_and_b32_e32 v101, 0xffff0000, v96
	v_lshlrev_b32_e32 v52, 16, v56
	v_and_b32_e32 v53, 0xffff0000, v56
	v_pk_mul_f32 v[100:101], v[100:101], v[52:53]
	s_nop 0
	v_cvt_pk_bf16_f32 v56, v100, v101
	v_lshlrev_b32_e32 v100, 16, v97
	v_and_b32_e32 v101, 0xffff0000, v97
	v_lshlrev_b32_e32 v52, 16, v57
	v_and_b32_e32 v53, 0xffff0000, v57
	v_pk_mul_f32 v[100:101], v[100:101], v[52:53]
	s_nop 0
	v_cvt_pk_bf16_f32 v57, v100, v101
	v_lshlrev_b32_e32 v100, 16, v98
	v_and_b32_e32 v101, 0xffff0000, v98
	v_lshlrev_b32_e32 v52, 16, v58
	v_and_b32_e32 v53, 0xffff0000, v58
	v_pk_mul_f32 v[100:101], v[100:101], v[52:53]
	s_nop 0
	v_cvt_pk_bf16_f32 v58, v100, v101
	v_lshlrev_b32_e32 v100, 16, v99
	v_and_b32_e32 v101, 0xffff0000, v99
	v_lshlrev_b32_e32 v52, 16, v59
	v_and_b32_e32 v53, 0xffff0000, v59
	v_pk_mul_f32 v[100:101], v[100:101], v[52:53]
	s_nop 0
	v_cvt_pk_bf16_f32 v59, v100, v101
	global_store_dwordx4 v129, v[56:59], s[88:89]
	s_waitcnt vmcnt(9) lgkmcnt(0)
	v_lshlrev_b32_e32 v100, 16, v44
	v_and_b32_e32 v101, 0xffff0000, v44
	v_lshlrev_b32_e32 v52, 16, v60
	v_and_b32_e32 v53, 0xffff0000, v60
	v_pk_mul_f32 v[100:101], v[100:101], v[52:53]
	s_nop 0
	v_cvt_pk_bf16_f32 v60, v100, v101
	v_lshlrev_b32_e32 v100, 16, v45
	v_and_b32_e32 v101, 0xffff0000, v45
	v_lshlrev_b32_e32 v52, 16, v61
	v_and_b32_e32 v53, 0xffff0000, v61
	v_pk_mul_f32 v[100:101], v[100:101], v[52:53]
	s_nop 0
	v_cvt_pk_bf16_f32 v61, v100, v101
	v_lshlrev_b32_e32 v100, 16, v46
	v_and_b32_e32 v101, 0xffff0000, v46
	v_lshlrev_b32_e32 v52, 16, v62
	v_and_b32_e32 v53, 0xffff0000, v62
	v_pk_mul_f32 v[100:101], v[100:101], v[52:53]
	s_nop 0
	v_cvt_pk_bf16_f32 v62, v100, v101
	v_lshlrev_b32_e32 v100, 16, v47
	v_and_b32_e32 v101, 0xffff0000, v47
	v_lshlrev_b32_e32 v52, 16, v63
	v_and_b32_e32 v53, 0xffff0000, v63
	v_pk_mul_f32 v[100:101], v[100:101], v[52:53]
	s_nop 0
	v_cvt_pk_bf16_f32 v63, v100, v101
	global_store_dwordx4 v127, v[60:63], s[88:89]
	ds_read_b128 v[96:99], v130 offset:128
	ds_read_b128 v[44:47], v130 offset:2304
	s_waitcnt vmcnt(9) lgkmcnt(1)
	v_lshlrev_b32_e32 v100, 16, v96
	v_and_b32_e32 v101, 0xffff0000, v96
	v_lshlrev_b32_e32 v52, 16, v64
	v_and_b32_e32 v53, 0xffff0000, v64
	v_pk_mul_f32 v[100:101], v[100:101], v[52:53]
	s_nop 0
	v_cvt_pk_bf16_f32 v64, v100, v101
	v_lshlrev_b32_e32 v100, 16, v97
	v_and_b32_e32 v101, 0xffff0000, v97
	v_lshlrev_b32_e32 v52, 16, v65
	v_and_b32_e32 v53, 0xffff0000, v65
	v_pk_mul_f32 v[100:101], v[100:101], v[52:53]
	s_nop 0
	v_cvt_pk_bf16_f32 v65, v100, v101
	v_lshlrev_b32_e32 v100, 16, v98
	v_and_b32_e32 v101, 0xffff0000, v98
	v_lshlrev_b32_e32 v52, 16, v66
	v_and_b32_e32 v53, 0xffff0000, v66
	v_pk_mul_f32 v[100:101], v[100:101], v[52:53]
	s_nop 0
	v_cvt_pk_bf16_f32 v66, v100, v101
	v_lshlrev_b32_e32 v100, 16, v99
	v_and_b32_e32 v101, 0xffff0000, v99
	v_lshlrev_b32_e32 v52, 16, v67
	v_and_b32_e32 v53, 0xffff0000, v67
	v_pk_mul_f32 v[100:101], v[100:101], v[52:53]
	s_nop 0
	v_cvt_pk_bf16_f32 v67, v100, v101
	global_store_dwordx4 v129, v[64:67], s[88:89] offset:128
	s_waitcnt vmcnt(9) lgkmcnt(0)
	v_lshlrev_b32_e32 v100, 16, v44
	v_and_b32_e32 v101, 0xffff0000, v44
	v_lshlrev_b32_e32 v52, 16, v68
	v_and_b32_e32 v53, 0xffff0000, v68
	v_pk_mul_f32 v[100:101], v[100:101], v[52:53]
	s_nop 0
	v_cvt_pk_bf16_f32 v68, v100, v101
	v_lshlrev_b32_e32 v100, 16, v45
	v_and_b32_e32 v101, 0xffff0000, v45
	v_lshlrev_b32_e32 v52, 16, v69
	v_and_b32_e32 v53, 0xffff0000, v69
	v_pk_mul_f32 v[100:101], v[100:101], v[52:53]
	s_nop 0
	v_cvt_pk_bf16_f32 v69, v100, v101
	v_lshlrev_b32_e32 v100, 16, v46
	v_and_b32_e32 v101, 0xffff0000, v46
	v_lshlrev_b32_e32 v52, 16, v70
	v_and_b32_e32 v53, 0xffff0000, v70
	v_pk_mul_f32 v[100:101], v[100:101], v[52:53]
	s_nop 0
	v_cvt_pk_bf16_f32 v70, v100, v101
	v_lshlrev_b32_e32 v100, 16, v47
	v_and_b32_e32 v101, 0xffff0000, v47
	v_lshlrev_b32_e32 v52, 16, v71
	v_and_b32_e32 v53, 0xffff0000, v71
	v_pk_mul_f32 v[100:101], v[100:101], v[52:53]
	s_nop 0
	v_cvt_pk_bf16_f32 v71, v100, v101
	global_store_dwordx4 v127, v[68:71], s[88:89] offset:128
	s_nop 1
	global_load_dwordx4 v[56:59], v251, s[10:11]
	global_load_dwordx4 v[60:63], v251, s[12:13]
	global_load_dwordx4 v[64:67], v251, s[14:15]
	global_load_dwordx4 v[68:71], v252, s[10:11]
	global_load_dwordx4 v[44:47], v252, s[12:13]
	global_load_dwordx4 v[48:51], v252, s[14:15]
	s_waitcnt vmcnt(13)
; __device__ __forceinline__ unsigned pk2(float lo, float hi) { const f32x2_t v = {lo, hi}; const bf16v2_t b = __builtin_convertvector(v, bf16v2_t); return __builtin_bit_cast(unsigned, b); }
; __device__ __forceinline__ float bflo(unsigned u) { return __uint_as_float(u << 16); }
; __device__ __forceinline__ float bfhi(unsigned u) { return __uint_as_float(u & 0xffff0000u); }
; __device__ __forceinline__ void ret_out_phase(const Args& A, Frame& F, int l, bool lastl, bf16_t* ARET, bf16_t* ALRU) {
;     ...
; #pragma unroll
;         for (int i = 0; i < 4; ++i) {
;             const int u = tid + i * NTHREADS, r = u >> 4, c8 = (u & 15) * 8;
;             const size_t o = (rowbase + r) * D + 128 * h + c8;
;             const u32x4 hf = *(const u32x4*)(WSB(WS_HF) + o), hb = *(const u32x4*)(WSB(WS_HB) + o), gg = *(const u32x4*)(WSB(WS_GG) + o);
;             u32x4 ov;
; #pragma unroll
;             for (int e = 0; e < 4; ++e) ov[e] = pk2((bflo(hf[e]) + bflo(hb[e])) * bflo(gg[e]), (bfhi(hf[e]) + bfhi(hb[e])) * bfhi(gg[e]));
;             *(u32x4*)(ALRU + o) = ov;
;         }
	v_lshlrev_b32_e32 v100, 16, v72
	v_and_b32_e32 v101, 0xffff0000, v72
	v_lshlrev_b32_e32 v52, 16, v76
	v_and_b32_e32 v53, 0xffff0000, v76
	v_pk_add_f32 v[100:101], v[100:101], v[52:53]
	v_lshlrev_b32_e32 v52, 16, v80
	v_and_b32_e32 v53, 0xffff0000, v80
	v_pk_mul_f32 v[100:101], v[100:101], v[52:53]
	s_nop 0
	v_cvt_pk_bf16_f32 v72, v100, v101
	v_lshlrev_b32_e32 v100, 16, v73
	v_and_b32_e32 v101, 0xffff0000, v73
	v_lshlrev_b32_e32 v52, 16, v77
	v_and_b32_e32 v53, 0xffff0000, v77
	v_pk_add_f32 v[100:101], v[100:101], v[52:53]
	v_lshlrev_b32_e32 v52, 16, v81
	v_and_b32_e32 v53, 0xffff0000, v81
	v_pk_mul_f32 v[100:101], v[100:101], v[52:53]
	s_nop 0
	v_cvt_pk_bf16_f32 v73, v100, v101
	v_lshlrev_b32_e32 v100, 16, v74
	v_and_b32_e32 v101, 0xffff0000, v74
	v_lshlrev_b32_e32 v52, 16, v78
	v_and_b32_e32 v53, 0xffff0000, v78
	v_pk_add_f32 v[100:101], v[100:101], v[52:53]
	v_lshlrev_b32_e32 v52, 16, v82
	v_and_b32_e32 v53, 0xffff0000, v82
	v_pk_mul_f32 v[100:101], v[100:101], v[52:53]
	s_nop 0
	v_cvt_pk_bf16_f32 v74, v100, v101
	v_lshlrev_b32_e32 v100, 16, v75
	v_and_b32_e32 v101, 0xffff0000, v75
	v_lshlrev_b32_e32 v52, 16, v79
	v_and_b32_e32 v53, 0xffff0000, v79
	v_pk_add_f32 v[100:101], v[100:101], v[52:53]
	v_lshlrev_b32_e32 v52, 16, v83
	v_and_b32_e32 v53, 0xffff0000, v83
	v_pk_mul_f32 v[100:101], v[100:101], v[52:53]
	s_nop 0
	v_cvt_pk_bf16_f32 v75, v100, v101
	global_store_dwordx4 v141, v[72:75], s[90:91]
	s_waitcnt vmcnt(11)
	v_lshlrev_b32_e32 v100, 16, v84
	v_and_b32_e32 v101, 0xffff0000, v84
	v_lshlrev_b32_e32 v52, 16, v88
	v_and_b32_e32 v53, 0xffff0000, v88
	v_pk_add_f32 v[100:101], v[100:101], v[52:53]
	v_lshlrev_b32_e32 v52, 16, v92
	v_and_b32_e32 v53, 0xffff0000, v92
	v_pk_mul_f32 v[100:101], v[100:101], v[52:53]
	s_nop 0
	v_cvt_pk_bf16_f32 v84, v100, v101
	v_lshlrev_b32_e32 v100, 16, v85
	v_and_b32_e32 v101, 0xffff0000, v85
	v_lshlrev_b32_e32 v52, 16, v89
	v_and_b32_e32 v53, 0xffff0000, v89
	v_pk_add_f32 v[100:101], v[100:101], v[52:53]
	v_lshlrev_b32_e32 v52, 16, v93
	v_and_b32_e32 v53, 0xffff0000, v93
	v_pk_mul_f32 v[100:101], v[100:101], v[52:53]
	s_nop 0
	v_cvt_pk_bf16_f32 v85, v100, v101
	v_lshlrev_b32_e32 v100, 16, v86
	v_and_b32_e32 v101, 0xffff0000, v86
	v_lshlrev_b32_e32 v52, 16, v90
	v_and_b32_e32 v53, 0xffff0000, v90
	v_pk_add_f32 v[100:101], v[100:101], v[52:53]
	v_lshlrev_b32_e32 v52, 16, v94
	v_and_b32_e32 v53, 0xffff0000, v94
	v_pk_mul_f32 v[100:101], v[100:101], v[52:53]
	s_nop 0
	v_cvt_pk_bf16_f32 v86, v100, v101
	v_lshlrev_b32_e32 v100, 16, v87
	v_and_b32_e32 v101, 0xffff0000, v87
	v_lshlrev_b32_e32 v52, 16, v91
	v_and_b32_e32 v53, 0xffff0000, v91
	v_pk_add_f32 v[100:101], v[100:101], v[52:53]
	v_lshlrev_b32_e32 v52, 16, v95
	v_and_b32_e32 v53, 0xffff0000, v95
	v_pk_mul_f32 v[100:101], v[100:101], v[52:53]
	s_nop 0
	v_cvt_pk_bf16_f32 v87, v100, v101
	global_store_dwordx4 v250, v[84:87], s[90:91]
	s_waitcnt vmcnt(5)
	v_lshlrev_b32_e32 v100, 16, v56
	v_and_b32_e32 v101, 0xffff0000, v56
	v_lshlrev_b32_e32 v52, 16, v60
	v_and_b32_e32 v53, 0xffff0000, v60
	v_pk_add_f32 v[100:101], v[100:101], v[52:53]
	v_lshlrev_b32_e32 v52, 16, v64
	v_and_b32_e32 v53, 0xffff0000, v64
	v_pk_mul_f32 v[100:101], v[100:101], v[52:53]
	s_nop 0
	v_cvt_pk_bf16_f32 v56, v100, v101
	v_lshlrev_b32_e32 v100, 16, v57
	v_and_b32_e32 v101, 0xffff0000, v57
	v_lshlrev_b32_e32 v52, 16, v61
	v_and_b32_e32 v53, 0xffff0000, v61
	v_pk_add_f32 v[100:101], v[100:101], v[52:53]
	v_lshlrev_b32_e32 v52, 16, v65
	v_and_b32_e32 v53, 0xffff0000, v65
	v_pk_mul_f32 v[100:101], v[100:101], v[52:53]
	s_nop 0
	v_cvt_pk_bf16_f32 v57, v100, v101
	v_lshlrev_b32_e32 v100, 16, v58
	v_and_b32_e32 v101, 0xffff0000, v58
	v_lshlrev_b32_e32 v52, 16, v62
	v_and_b32_e32 v53, 0xffff0000, v62
	v_pk_add_f32 v[100:101], v[100:101], v[52:53]
	v_lshlrev_b32_e32 v52, 16, v66
	v_and_b32_e32 v53, 0xffff0000, v66
	v_pk_mul_f32 v[100:101], v[100:101], v[52:53]
	s_nop 0
	v_cvt_pk_bf16_f32 v58, v100, v101
	v_lshlrev_b32_e32 v100, 16, v59
	v_and_b32_e32 v101, 0xffff0000, v59
	v_lshlrev_b32_e32 v52, 16, v63
	v_and_b32_e32 v53, 0xffff0000, v63
	v_pk_add_f32 v[100:101], v[100:101], v[52:53]
	v_lshlrev_b32_e32 v52, 16, v67
	v_and_b32_e32 v53, 0xffff0000, v67
	v_pk_mul_f32 v[100:101], v[100:101], v[52:53]
	s_nop 0
	v_cvt_pk_bf16_f32 v59, v100, v101
	global_store_dwordx4 v251, v[56:59], s[90:91]
	s_waitcnt vmcnt(3)
	v_lshlrev_b32_e32 v100, 16, v68
	v_and_b32_e32 v101, 0xffff0000, v68
	v_lshlrev_b32_e32 v52, 16, v44
	v_and_b32_e32 v53, 0xffff0000, v44
	v_pk_add_f32 v[100:101], v[100:101], v[52:53]
	v_lshlrev_b32_e32 v52, 16, v48
	v_and_b32_e32 v53, 0xffff0000, v48
	v_pk_mul_f32 v[100:101], v[100:101], v[52:53]
	s_nop 0
	v_cvt_pk_bf16_f32 v68, v100, v101
	v_lshlrev_b32_e32 v100, 16, v69
	v_and_b32_e32 v101, 0xffff0000, v69
	v_lshlrev_b32_e32 v52, 16, v45
	v_and_b32_e32 v53, 0xffff0000, v45
	v_pk_add_f32 v[100:101], v[100:101], v[52:53]
	v_lshlrev_b32_e32 v52, 16, v49
	v_and_b32_e32 v53, 0xffff0000, v49
	v_pk_mul_f32 v[100:101], v[100:101], v[52:53]
	s_nop 0
	v_cvt_pk_bf16_f32 v69, v100, v101
	v_lshlrev_b32_e32 v100, 16, v70
	v_and_b32_e32 v101, 0xffff0000, v70
	v_lshlrev_b32_e32 v52, 16, v46
	v_and_b32_e32 v53, 0xffff0000, v46
	v_pk_add_f32 v[100:101], v[100:101], v[52:53]
	v_lshlrev_b32_e32 v52, 16, v50
	v_and_b32_e32 v53, 0xffff0000, v50
	v_pk_mul_f32 v[100:101], v[100:101], v[52:53]
	s_nop 0
	v_cvt_pk_bf16_f32 v70, v100, v101
	v_lshlrev_b32_e32 v100, 16, v71
	v_and_b32_e32 v101, 0xffff0000, v71
	v_lshlrev_b32_e32 v52, 16, v47
	v_and_b32_e32 v53, 0xffff0000, v47
	v_pk_add_f32 v[100:101], v[100:101], v[52:53]
	v_lshlrev_b32_e32 v52, 16, v51
	v_and_b32_e32 v53, 0xffff0000, v51
	v_pk_mul_f32 v[100:101], v[100:101], v[52:53]
	s_nop 0
	v_cvt_pk_bf16_f32 v71, v100, v101
	global_store_dwordx4 v252, v[68:71], s[90:91]
	s_cbranch_scc1 .LBB0_30

; #define LAS __attribute__((address_space(3)))
; __device__ __forceinline__ void cvt_load(const Frame& F, const CvtMat& m, int tt, f32x4 (&v)[4]) {
;     const int nb = m.N >> 7, kb = tt / nb, nbk = tt - kb * nb, k0 = kb * 64, n0 = nbk * 128;
;     const int src = srccol(m.kind, n0 + (F.tid & 31) * 4);
; #pragma unroll
;     for (int i = 0; i < 4; ++i) v[i] = *(const f32x4*)(m.W + (size_t)(k0 + (F.tid >> 5) + 16 * i) * m.N + src);
; }
; __device__ __forceinline__ void cvt_store(const Frame& F, const CvtMat& m, int tt, const f32x4 (&v)[4]) {
;     LAS float* tile = (LAS float*)F.lds;
;     const int nb = m.N >> 7, kb = tt / nb, nbk = tt - kb * nb, k0 = kb * 64, n0 = nbk * 128;
;     const int tid = F.tid;
; #pragma unroll
;     for (int i = 0; i < 4; ++i) {
;         const int kk = (tid >> 5) + 16 * i, nn = (tid & 31) * 4;
;         tile[kk * 129 + nn] = v[i][0]; tile[kk * 129 + nn + 1] = v[i][1]; tile[kk * 129 + nn + 2] = v[i][2]; tile[kk * 129 + nn + 3] = v[i][3];
;     }
;     __syncthreads();
;     {
;         const int n = tid >> 2, ks = (tid & 3) * 16;
;         u32x4 o0, o1;
; #pragma unroll
;         for (int i = 0; i < 4; ++i) o0[i] = pk2(tile[(ks + 2 * i) * 129 + n], tile[(ks + 2 * i + 1) * 129 + n]);
; #pragma unroll
;         for (int i = 0; i < 4; ++i) o1[i] = pk2(tile[(ks + 8 + 2 * i) * 129 + n], tile[(ks + 8 + 2 * i + 1) * 129 + n]);
;         bf16_t* dst = m.Bt + (size_t)(n0 + n) * m.K + k0 + ks;
;         *(u32x4*)dst = o0; *(u32x4*)(dst + 8) = o1;
;     }
;     __syncthreads();
; }
; __device__ __forceinline__ void convert_layer(const Args& A, Frame& F, int l) {
;     refresh(F);
;     constexpr int NT = 2 * 16 * 44 + 2 * 44 * 8 + 16 * 56 + 3 * 16 * 8;
;     const int nmy = (NT - F.bid + F.G - 1) / F.G;
;     f32x4 v[4];
;     { CvtMat m; int tt; cvt_pick(A, F, l, F.bid, m, tt); cvt_load(F, m, tt, v); }
;     for (int j = 0; j < nmy; ++j) {
;         const int it = F.bid + j * F.G, itn = (j + 1 < nmy) ? it + F.G : it;
;         f32x4 vn[4];
;         { CvtMat mn; int ttn; cvt_pick(A, F, l, itn, mn, ttn); cvt_load(F, mn, ttn, vn); }
;         { CvtMat m; int tt; cvt_pick(A, F, l, it, m, tt); cvt_store(F, m, tt, v); }
; #pragma unroll
;         for (int i = 0; i < 4; ++i) v[i] = vn[i];
;     }
.LBB0_605:
	s_abs_i32 s2, s34
	v_cvt_f32_u32_e32 v3, s2
	s_sub_i32 s10, s34, s38
	s_add_i32 s11, s10, 0xd3f
	s_sub_i32 s10, 0xfffff2c1, s10
	v_rcp_iflag_f32_e32 v3, v3
	s_xor_b32 s13, s11, s34
	s_sub_i32 s12, 0, s2
	s_max_i32 s10, s11, s10
	v_mul_f32_e32 v3, 0x4f7ffffe, v3
	v_cvt_u32_f32_e32 v3, v3
	s_ashr_i32 s11, s13, 31
	v_readfirstlane_b32 s13, v3
	s_mul_i32 s12, s12, s13
	s_mul_hi_u32 s12, s13, s12
	s_add_i32 s13, s13, s12
	s_mul_hi_u32 s12, s10, s13
	s_mul_i32 s13, s12, s2
	s_sub_i32 s10, s10, s13
	s_add_i32 s15, s12, 1
	s_sub_i32 s13, s10, s2
	s_cmp_ge_u32 s10, s2
	s_cselect_b32 s12, s15, s12
	s_cselect_b32 s10, s13, s10
	s_add_i32 s13, s12, 1
	s_cmp_ge_u32 s10, s2
	s_cselect_b32 s2, s13, s12
	s_xor_b32 s2, s2, s11
	s_sub_i32 s2, s2, s11
	s_cmp_lt_i32 s2, 1
	s_cbranch_scc1 .LBB0_691
	s_mul_hi_u32 s11, s4, s44
	s_mul_i32 s10, s4, s44
	s_lshl_b64 s[10:11], s[10:11], 2
	v_ashrrev_i32_e32 v35, 5, v0
	s_waitcnt lgkmcnt(0)
	s_add_u32 s8, s8, s10
	v_lshl_add_u32 v14, s14, 6, v35
	s_addc_u32 s9, s9, s11
	v_mad_i64_i32 v[4:5], s[10:11], v14, s5, 0
	v_ashrrev_i32_e32 v3, 31, v2
	v_lshl_add_u64 v[4:5], v[4:5], 2, s[8:9]
	v_lshlrev_b64 v[10:11], 2, v[2:3]
	v_lshl_add_u64 v[2:3], v[4:5], 0, v[10:11]
	v_add_u32_e32 v4, 16, v14
	v_add_u32_e32 v12, 32, v14
	v_add_u32_e32 v14, 48, v14
	v_mad_i64_i32 v[4:5], s[10:11], s5, v4, 0
	v_mad_i64_i32 v[12:13], s[10:11], s5, v12, 0
	v_mad_i64_i32 v[14:15], s[4:5], s5, v14, 0
	v_lshl_add_u64 v[4:5], v[4:5], 2, s[8:9]
	v_lshl_add_u64 v[12:13], v[12:13], 2, s[8:9]
	v_lshl_add_u64 v[14:15], v[14:15], 2, s[8:9]
	v_lshl_add_u64 v[6:7], v[4:5], 0, v[10:11]
	v_lshl_add_u64 v[12:13], v[12:13], 0, v[10:11]
	v_lshl_add_u64 v[14:15], v[14:15], 0, v[10:11]
	global_load_dwordx4 v[2:5], v[2:3], off
	s_nop 0
	global_load_dwordx4 v[6:9], v[6:7], off
	s_nop 0
	global_load_dwordx4 v[10:13], v[12:13], off
	s_nop 0
	global_load_dwordx4 v[14:17], v[14:15], off
	v_lshlrev_b32_e32 v22, 3, v0
	v_and_b32_e32 v22, 56, v22
	v_ashrrev_i32_e32 v36, 3, v0
	v_mul_u32_u24_e32 v25, 0x204, v22
	v_lshrrev_b32_e32 v0, 1, v0
	v_and_b32_e32 v0, -4, v0
	v_add3_u32 v37, 0, v25, v0
	v_lshrrev_b32_e32 v0, 1, v18
	s_movk_i32 s4, 0x204
	v_and_b32_e32 v0, 16, v0
	v_lshl_add_u32 v23, v34, 2, 0
	v_mul_lo_u32 v24, v35, s4
	v_and_or_b32 v38, v21, 32, v0
	v_and_b32_e32 v0, 0x60, v18
	v_or_b32_e32 v39, v20, v19
	v_or3_b32 v40, v0, v19, v20
	s_mov_b32 s20, 0
	v_add_u32_e32 v41, v23, v24
	v_lshlrev_b32_e32 v0, 1, v22
	s_mov_b32 s26, s38
	s_branch .LBB0_608
.LBB0_607:
	s_waitcnt vmcnt(7)
	ds_write2_b32 v41, v2, v3 offset1:1
	ds_write2_b32 v41, v4, v5 offset0:2 offset1:3
	v_add_u32_e32 v2, 0x2040, v41
	s_waitcnt vmcnt(6)
	ds_write2_b32 v2, v6, v7 offset1:1
	v_add_u32_e32 v2, 0x2048, v41
	ds_write2_b32 v2, v8, v9 offset1:1
	v_add_u32_e32 v2, 0x4080, v41
	s_waitcnt vmcnt(5)
	ds_write2_b32 v2, v10, v11 offset1:1
	v_add_u32_e32 v2, 0x4088, v41
	ds_write2_b32 v2, v12, v13 offset1:1
	v_add_u32_e32 v2, 0x60c0, v41
	s_waitcnt vmcnt(4)
	ds_write2_b32 v2, v14, v15 offset1:1
	v_add_u32_e32 v2, 0x60c8, v41
	v_add_u32_e32 v4, 0x400, v37
	v_add_u32_e32 v6, 0x800, v37
	ds_write2_b32 v2, v16, v17 offset1:1
	s_waitcnt lgkmcnt(0)
	s_barrier
	ds_read2_b32 v[2:3], v37 offset1:129
	ds_read2_b32 v[4:5], v4 offset0:2 offset1:131
	ds_read2_b32 v[6:7], v6 offset0:4 offset1:133
	v_add_u32_e32 v8, 0xc00, v37
	ds_read2_b32 v[8:9], v8 offset0:6 offset1:135
	v_add_u32_e32 v10, 0, v37
	ds_read2_b32 v[10:11], v10 offset0:64 offset1:193
	s_waitcnt lgkmcnt(4)
	v_cvt_pk_bf16_f32 v2, v2, v3
	s_waitcnt lgkmcnt(3)
	v_cvt_pk_bf16_f32 v3, v4, v5
	s_waitcnt lgkmcnt(2)
	v_cvt_pk_bf16_f32 v4, v6, v7
	v_add_u32_e32 v7, 0x400, v37
	s_waitcnt lgkmcnt(1)
	v_cvt_pk_bf16_f32 v5, v8, v9
	ds_read2_b32 v[8:9], v7 offset0:66 offset1:195
	v_add_u32_e32 v7, 0x800, v37
	s_waitcnt lgkmcnt(1)
	v_cvt_pk_bf16_f32 v6, v10, v11
	ds_read2_b32 v[10:11], v7 offset0:68 offset1:197
	v_add_u32_e32 v7, 0xc00, v37
	ds_read2_b32 v[12:13], v7 offset0:70 offset1:199
	v_cvt_f32_ubyte0_e32 v7, s10
	v_rcp_iflag_f32_e32 v14, v7
	s_waitcnt lgkmcnt(2)
	v_cvt_pk_bf16_f32 v7, v8, v9
	s_waitcnt lgkmcnt(1)
	v_cvt_pk_bf16_f32 v8, v10, v11
	s_add_u32 s4, s30, s4
	v_mul_f32_e32 v10, 0x4f7ffffe, v14
	v_cvt_u32_f32_e32 v10, v10
	s_addc_u32 s5, s31, s5
	s_and_b32 s8, s14, 13
	s_cmp_eq_u32 s8, 1
	s_cselect_b32 s9, s22, 0x400
	s_lshl_b32 s100, s9, 7
	s_sub_i32 s13, 0, s10
	v_readfirstlane_b32 s14, v10
	s_mul_i32 s13, s13, s14
	s_add_i32 s8, s11, s26
	s_mul_hi_u32 s13, s14, s13
	s_abs_i32 s12, s8
	s_add_i32 s14, s14, s13
	s_mul_hi_u32 s13, s12, s14
	s_mul_i32 s14, s13, s10
	s_sub_i32 s12, s12, s14
	s_ashr_i32 s11, s8, 31
	s_add_i32 s14, s13, 1
	s_sub_i32 s15, s12, s10
	s_cmp_ge_u32 s12, s10
	s_cselect_b32 s13, s14, s13
	s_cselect_b32 s12, s15, s12
	s_add_i32 s14, s13, 1
	s_cmp_ge_u32 s12, s10
	s_cselect_b32 s12, s14, s13
	s_xor_b32 s12, s12, s11
	s_sub_i32 s11, s12, s11
	s_mul_i32 s10, s10, s11
	s_sub_i32 s10, s8, s10
	v_lshl_add_u32 v10, s10, 7, v36
	s_lshl_b32 s8, s11, 6
	v_mad_i64_i32 v[10:11], s[10:11], s9, v10, 0
	v_lshl_add_u64 v[10:11], v[10:11], 1, s[4:5]
	s_ashr_i32 s9, s8, 31
	v_lshl_add_u64 v[10:11], s[8:9], 1, v[10:11]
	s_waitcnt lgkmcnt(0)
	v_cvt_pk_bf16_f32 v9, v12, v13
	v_lshl_add_u64 v[10:11], v[10:11], 0, v[0:1]
	s_add_i32 s26, s26, s34
	v_add_co_u32_e64 v12, s[98:99], s100, v10
	s_nop 1
	v_addc_co_u32_e64 v13, s[98:99], 0, v11, s[98:99]
	global_store_dwordx4 v[10:11], v[2:5], off
	global_store_dwordx4 v[12:13], v[6:9], off
	s_cmp_lg_u32 s2, s20
	s_waitcnt vmcnt(5)
	v_mov_b32_e32 v2, v22
	v_mov_b32_e32 v3, v23
	v_mov_b32_e32 v4, v24
	v_mov_b32_e32 v5, v25
	s_waitcnt vmcnt(4)
	v_mov_b32_e32 v6, v18
	v_mov_b32_e32 v7, v19
	v_mov_b32_e32 v8, v20
	v_mov_b32_e32 v9, v21
	s_waitcnt vmcnt(3)
	v_mov_b32_e32 v10, v30
	v_mov_b32_e32 v11, v31
	v_mov_b32_e32 v12, v32
	v_mov_b32_e32 v13, v33
	s_waitcnt vmcnt(2)
	v_mov_b32_e32 v14, v26
	v_mov_b32_e32 v15, v27
	v_mov_b32_e32 v16, v28
	v_mov_b32_e32 v17, v29
	s_barrier
	s_cbranch_scc0 .LBB0_691

; #define LAS __attribute__((address_space(3)))
; __device__ __forceinline__ void cvt_load(const Frame& F, const CvtMat& m, int tt, f32x4 (&v)[4]) {
;     const int nb = m.N >> 7, kb = tt / nb, nbk = tt - kb * nb, k0 = kb * 64, n0 = nbk * 128;
;     const int src = srccol(m.kind, n0 + (F.tid & 31) * 4);
; #pragma unroll
;     for (int i = 0; i < 4; ++i) v[i] = *(const f32x4*)(m.W + (size_t)(k0 + (F.tid >> 5) + 16 * i) * m.N + src);
; }
; __device__ __forceinline__ void cvt_store(const Frame& F, const CvtMat& m, int tt, const f32x4 (&v)[4]) {
;     LAS float* tile = (LAS float*)F.lds;
;     const int nb = m.N >> 7, kb = tt / nb, nbk = tt - kb * nb, k0 = kb * 64, n0 = nbk * 128;
;     const int tid = F.tid;
; #pragma unroll
;     for (int i = 0; i < 4; ++i) {
;         const int kk = (tid >> 5) + 16 * i, nn = (tid & 31) * 4;
;         tile[kk * 129 + nn] = v[i][0]; tile[kk * 129 + nn + 1] = v[i][1]; tile[kk * 129 + nn + 2] = v[i][2]; tile[kk * 129 + nn + 3] = v[i][3];
;     }
;     __syncthreads();
;     {
;         const int n = tid >> 2, ks = (tid & 3) * 16;
;         u32x4 o0, o1;
; #pragma unroll
;         for (int i = 0; i < 4; ++i) o0[i] = pk2(tile[(ks + 2 * i) * 129 + n], tile[(ks + 2 * i + 1) * 129 + n]);
; #pragma unroll
;         for (int i = 0; i < 4; ++i) o1[i] = pk2(tile[(ks + 8 + 2 * i) * 129 + n], tile[(ks + 8 + 2 * i + 1) * 129 + n]);
;         bf16_t* dst = m.Bt + (size_t)(n0 + n) * m.K + k0 + ks;
;         *(u32x4*)dst = o0; *(u32x4*)(dst + 8) = o1;
;     }
;     __syncthreads();
; }
; __device__ __forceinline__ void convert_layer(const Args& A, Frame& F, int l) {
;     refresh(F);
;     constexpr int NT = 2 * 16 * 44 + 2 * 44 * 8 + 16 * 56 + 3 * 16 * 8;
;     const int nmy = (NT - F.bid + F.G - 1) / F.G;
;     f32x4 v[4];
;     { CvtMat m; int tt; cvt_pick(A, F, l, F.bid, m, tt); cvt_load(F, m, tt, v); }
;     for (int j = 0; j < nmy; ++j) {
;         const int it = F.bid + j * F.G, itn = (j + 1 < nmy) ? it + F.G : it;
;         f32x4 vn[4];
;         { CvtMat mn; int ttn; cvt_pick(A, F, l, itn, mn, ttn); cvt_load(F, mn, ttn, vn); }
;         { CvtMat m; int tt; cvt_pick(A, F, l, it, m, tt); cvt_store(F, m, tt, v); }
; #pragma unroll
;         for (int i = 0; i < 4; ++i) v[i] = vn[i];
;     }
.LBB0_777:
	s_abs_i32 s6, s34
	v_cvt_f32_u32_e32 v3, s6
	s_ashr_i32 s18, s2, 6
	s_sub_i32 s2, s34, s38
	s_add_i32 s7, s2, 0xd3f
	v_rcp_iflag_f32_e32 v3, v3
	s_sub_i32 s2, 0xfffff2c1, s2
	s_xor_b32 s9, s7, s34
	s_sub_i32 s8, 0, s6
	v_mul_f32_e32 v3, 0x4f7ffffe, v3
	v_cvt_u32_f32_e32 v3, v3
	s_max_i32 s2, s7, s2
	s_ashr_i32 s7, s9, 31
	v_and_b32_e32 v142, 63, v0
	v_readfirstlane_b32 s9, v3
	s_mul_i32 s8, s8, s9
	s_mul_hi_u32 s8, s9, s8
	s_add_i32 s9, s9, s8
	s_mul_hi_u32 s8, s2, s9
	s_mul_i32 s9, s8, s6
	s_sub_i32 s2, s2, s9
	s_add_i32 s11, s8, 1
	s_sub_i32 s9, s2, s6
	s_cmp_ge_u32 s2, s6
	s_cselect_b32 s8, s11, s8
	s_cselect_b32 s2, s9, s2
	s_add_i32 s9, s8, 1
	s_cmp_ge_u32 s2, s6
	s_cselect_b32 s2, s9, s8
	s_xor_b32 s2, s2, s7
	s_sub_i32 s2, s2, s7
	s_cmp_lt_i32 s2, 1
	s_cbranch_scc1 .LBB0_857
	v_ashrrev_i32_e32 v35, 5, v0
	v_lshl_add_u32 v14, s10, 6, v35
	v_mad_i64_i32 v[4:5], s[6:7], v14, s12, 0
	v_ashrrev_i32_e32 v3, 31, v2
	s_waitcnt lgkmcnt(0)
	v_lshl_add_u64 v[4:5], v[4:5], 2, s[4:5]
	v_lshlrev_b64 v[10:11], 2, v[2:3]
	v_lshl_add_u64 v[2:3], v[4:5], 0, v[10:11]
	v_add_u32_e32 v4, 16, v14
	v_add_u32_e32 v12, 32, v14
	v_add_u32_e32 v14, 48, v14
	v_mad_i64_i32 v[4:5], s[6:7], s12, v4, 0
	v_mad_i64_i32 v[12:13], s[6:7], s12, v12, 0
	v_mad_i64_i32 v[14:15], s[6:7], s12, v14, 0
	v_lshl_add_u64 v[4:5], v[4:5], 2, s[4:5]
	v_lshl_add_u64 v[12:13], v[12:13], 2, s[4:5]
	v_lshl_add_u64 v[14:15], v[14:15], 2, s[4:5]
	v_lshl_add_u64 v[6:7], v[4:5], 0, v[10:11]
	v_lshl_add_u64 v[12:13], v[12:13], 0, v[10:11]
	v_lshl_add_u64 v[14:15], v[14:15], 0, v[10:11]
	global_load_dwordx4 v[2:5], v[2:3], off
	s_nop 0
	global_load_dwordx4 v[6:9], v[6:7], off
	s_nop 0
	global_load_dwordx4 v[10:13], v[12:13], off
	s_nop 0
	global_load_dwordx4 v[14:17], v[14:15], off
	v_lshlrev_b32_e32 v22, 3, v0
	v_and_b32_e32 v22, 56, v22
	v_ashrrev_i32_e32 v36, 3, v0
	v_mul_u32_u24_e32 v25, 0x204, v22
	v_lshrrev_b32_e32 v0, 1, v0
	v_and_b32_e32 v0, -4, v0
	v_add3_u32 v37, 0, v25, v0
	v_lshrrev_b32_e32 v0, 1, v18
	s_movk_i32 s4, 0x204
	v_and_b32_e32 v0, 16, v0
	v_lshl_add_u32 v23, v34, 2, 0
	v_mul_lo_u32 v24, v35, s4
	v_and_or_b32 v38, v21, 32, v0
	v_and_b32_e32 v0, 0x60, v18
	v_or_b32_e32 v39, v20, v19
	v_or3_b32 v40, v0, v19, v20
	s_mov_b32 s12, 0
	v_add_u32_e32 v41, v23, v24
	v_lshlrev_b32_e32 v0, 1, v22
	s_branch .LBB0_780
.LBB0_779:
	s_waitcnt vmcnt(7)
	ds_write2_b32 v41, v2, v3 offset1:1
	ds_write2_b32 v41, v4, v5 offset0:2 offset1:3
	v_add_u32_e32 v2, 0x2040, v41
	s_waitcnt vmcnt(6)
	ds_write2_b32 v2, v6, v7 offset1:1
	v_add_u32_e32 v2, 0x2048, v41
	ds_write2_b32 v2, v8, v9 offset1:1
	v_add_u32_e32 v2, 0x4080, v41
	s_waitcnt vmcnt(5)
	ds_write2_b32 v2, v10, v11 offset1:1
	v_add_u32_e32 v2, 0x4088, v41
	ds_write2_b32 v2, v12, v13 offset1:1
	v_add_u32_e32 v2, 0x60c0, v41
	s_waitcnt vmcnt(4)
	ds_write2_b32 v2, v14, v15 offset1:1
	v_add_u32_e32 v2, 0x60c8, v41
	v_add_u32_e32 v4, 0x400, v37
	v_add_u32_e32 v6, 0x800, v37
	ds_write2_b32 v2, v16, v17 offset1:1
	s_waitcnt lgkmcnt(0)
	s_barrier
	ds_read2_b32 v[2:3], v37 offset1:129
	ds_read2_b32 v[4:5], v4 offset0:2 offset1:131
	ds_read2_b32 v[6:7], v6 offset0:4 offset1:133
	v_add_u32_e32 v8, 0xc00, v37
	ds_read2_b32 v[8:9], v8 offset0:6 offset1:135
	v_add_u32_e32 v10, 0, v37
	ds_read2_b32 v[10:11], v10 offset0:64 offset1:193
	s_waitcnt lgkmcnt(4)
	v_cvt_pk_bf16_f32 v2, v2, v3
	s_waitcnt lgkmcnt(3)
	v_cvt_pk_bf16_f32 v3, v4, v5
	s_waitcnt lgkmcnt(2)
	v_cvt_pk_bf16_f32 v4, v6, v7
	v_add_u32_e32 v7, 0x400, v37
	s_waitcnt lgkmcnt(1)
	v_cvt_pk_bf16_f32 v5, v8, v9
	ds_read2_b32 v[8:9], v7 offset0:66 offset1:195
	v_add_u32_e32 v7, 0x800, v37
	s_waitcnt lgkmcnt(1)
	v_cvt_pk_bf16_f32 v6, v10, v11
	ds_read2_b32 v[10:11], v7 offset0:68 offset1:197
	v_add_u32_e32 v7, 0xc00, v37
	ds_read2_b32 v[12:13], v7 offset0:70 offset1:199
	v_cvt_f32_ubyte0_e32 v7, s8
	v_rcp_iflag_f32_e32 v14, v7
	s_waitcnt lgkmcnt(2)
	v_cvt_pk_bf16_f32 v7, v8, v9
	s_waitcnt lgkmcnt(1)
	v_cvt_pk_bf16_f32 v8, v10, v11
	s_add_u32 s4, s30, s4
	v_mul_f32_e32 v10, 0x4f7ffffe, v14
	v_cvt_u32_f32_e32 v10, v10
	s_addc_u32 s5, s31, s5
	s_and_b32 s6, s13, 13
	s_cmp_eq_u32 s6, 1
	s_cselect_b32 s7, s22, 0x400
	s_lshl_b32 s100, s7, 7
	s_sub_i32 s11, 0, s8
	v_readfirstlane_b32 s13, v10
	s_mul_i32 s11, s11, s13
	s_add_i32 s6, s9, s38
	s_mul_hi_u32 s11, s13, s11
	s_abs_i32 s10, s6
	s_add_i32 s13, s13, s11
	s_mul_hi_u32 s11, s10, s13
	s_mul_i32 s13, s11, s8
	s_sub_i32 s10, s10, s13
	s_ashr_i32 s9, s6, 31
	s_add_i32 s13, s11, 1
	s_sub_i32 s14, s10, s8
	s_cmp_ge_u32 s10, s8
	s_cselect_b32 s11, s13, s11
	s_cselect_b32 s10, s14, s10
	s_add_i32 s13, s11, 1
	s_cmp_ge_u32 s10, s8
	s_cselect_b32 s10, s13, s11
	s_xor_b32 s10, s10, s9
	s_sub_i32 s9, s10, s9
	s_mul_i32 s8, s8, s9
	s_sub_i32 s8, s6, s8
	v_lshl_add_u32 v10, s8, 7, v36
	s_lshl_b32 s6, s9, 6
	v_mad_i64_i32 v[10:11], s[8:9], s7, v10, 0
	v_lshl_add_u64 v[10:11], v[10:11], 1, s[4:5]
	s_ashr_i32 s7, s6, 31
	v_lshl_add_u64 v[10:11], s[6:7], 1, v[10:11]
	s_waitcnt lgkmcnt(0)
	v_cvt_pk_bf16_f32 v9, v12, v13
	v_lshl_add_u64 v[10:11], v[10:11], 0, v[0:1]
	s_add_i32 s38, s38, s34
	v_add_co_u32_e64 v12, s[98:99], s100, v10
	s_nop 1
	v_addc_co_u32_e64 v13, s[98:99], 0, v11, s[98:99]
	global_store_dwordx4 v[10:11], v[2:5], off
	global_store_dwordx4 v[12:13], v[6:9], off
	s_cmp_eq_u32 s2, s12
	s_waitcnt vmcnt(5)
	v_mov_b32_e32 v2, v22
	v_mov_b32_e32 v3, v23
	v_mov_b32_e32 v4, v24
	v_mov_b32_e32 v5, v25
	s_waitcnt vmcnt(4)
	v_mov_b32_e32 v6, v18
	v_mov_b32_e32 v7, v19
	v_mov_b32_e32 v8, v20
	v_mov_b32_e32 v9, v21
	s_waitcnt vmcnt(3)
	v_mov_b32_e32 v10, v30
	v_mov_b32_e32 v11, v31
	v_mov_b32_e32 v12, v32
	v_mov_b32_e32 v13, v33
	s_waitcnt vmcnt(2)
	v_mov_b32_e32 v14, v26
	v_mov_b32_e32 v15, v27
	v_mov_b32_e32 v16, v28
	v_mov_b32_e32 v17, v29
	s_barrier
	s_cbranch_scc1 .LBB0_857
